# cand2 + ffn_out epilogue load stream two row groups ahead (counted waits) + both wave halves aligned around the w_out/ffn_out epilogues
# speedup vs baseline: 1.0026x; 1.0026x over previous
; #define LAS __attribute__((address_space(3)))
; __global__ void __launch_bounds__(NWAVES * 64, 2) skel_fwd(Args args) {
;     extern __shared__ __attribute__((aligned(16))) unsigned char lds[];
;     Frame F;
;     F.lds = (LAS unsigned char*)lds;
;     F.MISC = (volatile LAS unsigned*)(F.lds + MISC_OFF);
;     F.tid = threadIdx.x; F.lane = F.tid & 63; F.wave = __builtin_amdgcn_readfirstlane(F.tid >> 6);
;     F.G = gridDim.x; { const int bx = blockIdx.x; F.vcu = (F.G % 8 == 0) ? (bx % 8) * (F.G / 8) + bx / 8 : bx; }
_Z8skel_fwd4Args:
	v_readfirstlane_b32 s100, v0
	s_nop 3
	s_lshr_b32 s100, s100, 8
	s_load_dword s76, s[0:1], 0x98
	s_mov_b32 s73, s2
	s_add_u32 s2, s0, 0x98
	s_addc_u32 s3, s1, 0
	s_mov_b32 s78, s73
	v_writelane_b32 v243, s2, 0
	s_nop 1
	v_writelane_b32 v243, s3, 1
	s_waitcnt lgkmcnt(0)
	s_and_b32 s2, s76, 7
	s_cmp_lg_u32 s2, 0
	s_cbranch_scc1 .LBB0_2
	s_ashr_i32 s3, s73, 31
	s_lshr_b32 s3, s3, 29
	s_add_i32 s3, s73, s3
	s_and_b32 s4, s3, -8
	s_ashr_i32 s2, s76, 3
	s_sub_i32 s4, s73, s4
	s_mul_i32 s2, s2, s4
	s_ashr_i32 s3, s3, 3
	s_add_i32 s78, s2, s3

; #define PG8_BAR __builtin_amdgcn_s_barrier()
; template <class Epi, class Sched, bool ALIGN_EPI = false, bool SP2 = false>
; __device__ __forceinline__ void gemm_phase(PG8_LAS unsigned char* lds, const Gemm g, const Sched& S, const Epi& E) {
;     ...
;     for (;;) {
;         const bool has_next = S.next(ui + 1, nxt);
;         const char* nA = has_next ? (const char*)g.A + (size_t)nxt.pm * tstep : cA; const char* nB = has_next ? (const char*)g.Bt + (size_t)nxt.pn * tstep : cB;
;     ...
;         if constexpr (ALIGN_EPI) { if (wr == 1) PG8_BAR; }
.LBB0_547:
	s_or_b64 exec, exec, s[4:5]
	s_and_b64 vcc, exec, s[2:3]
	s_mov_b32 s33, s48
	s_mov_b32 s29, s50
	s_mov_b64 s[6:7], s[54:55]
	s_mov_b64 s[4:5], s[52:53]
	s_cbranch_vccnz .LBB0_572
	s_cmp_eq_u32 s100, 0
	s_cbranch_scc1 .Lal_0
	s_barrier

; #define PG8_STAGE(bufoff, gbase, voff) do { const char* gb_ = (const char*)(gbase); asm volatile("" : "+s"(gb_)); _Pragma("unroll") for (int _i = 0; _i < 2; ++_i) { unsigned vo_ = (voff)[_i]; asm volatile("" : "+v"(vo_));        \
;         __builtin_amdgcn_global_load_lds((const unsigned*)(gb_ + vo_), (PG8_LAS unsigned*)(lds + (bufoff) + ldsw + _i * 8192), 16, 0, 0); } } while (0)
; #define PG8_LDA(dst, b, h) do { _Pragma("unroll") for (int m = 0; m < 4; ++m) _Pragma("unroll") for (int k = 0; k < 2; ++k) dst[m][k] = *(const PG8_LAS bf16x8*)(lds + PG8_SA(b, h) + aoff + m * 2048 + k * 1024); } while (0)
; #define PG8_LDB(dst, b, h) do { _Pragma("unroll") for (int n = 0; n < 2; ++n) _Pragma("unroll") for (int k = 0; k < 2; ++k) dst[n][k] = *(const PG8_LAS bf16x8*)(lds + PG8_SB(b, h) + boff + n * 2048 + k * 1024); } while (0)
; #define PG8_MMA(ai, bj, At, Bt) do { __builtin_amdgcn_s_setprio(1); _Pragma("unroll") for (int m = 0; m < 4; ++m) _Pragma("unroll") for (int n = 0; n < 2; ++n) _Pragma("unroll") for (int k = 0; k < 2; ++k) \
;         acc[ai][bj][m][n] = __builtin_amdgcn_mfma_f32_16x16x32_bf16(Bt[n][k], At[m][k], acc[ai][bj][m][n], 0, 0, 0); __builtin_amdgcn_s_setprio(0); } while (0)
; #define PG8_WAIT_V(n) asm volatile("s_waitcnt vmcnt(" #n ")" ::: "memory")
; template <class Epi, class Sched, bool ALIGN_EPI = false, bool SP2 = false>
; __device__ __forceinline__ void gemm_phase(PG8_LAS unsigned char* lds, const Gemm g, const Sched& S, const Epi& E) {
;     ...
;             const bool last = (t == nt - 2);
;             const char* a1 = cA + (size_t)(t + 1) * kstep;
;             const char* a2 = last ? nA : cA + (size_t)(t + 2) * kstep; const char* b2 = last ? nB : cB + (size_t)(t + 2) * kstep;
;             const char* a3 = a2 + kstep; const char* b3 = b2 + kstep;
;             if (last && has_next) S.a_ready(nxt);
;             if constexpr (SP2) {
;             PG8_LDB(B0, 0, 0); PG8_LDB(B1, 0, 1); PG8_SCHED; PG8_LDA(At, 0, 0); PG8_STAGE(PG8_SA(1, 1), a1 + hstep, voffA);
;             PG8_WAIT_V(8); PG8_WAIT_L(0); PG8_BAR; PG8_MMA(0, 0, At, B0); PG8_MMA(0, 1, At, B1); PG8_BAR; PG8_SCHED;
;             PG8_LDA(At, 0, 1); PG8_STAGE(PG8_SB(0, 0), b2, voffB); PG8_STAGE(PG8_SB(0, 1), b2 + hstep, voffB); PG8_STAGE(PG8_SA(0, 0), a2, voffA);
;             PG8_WAIT_V(8); PG8_WAIT_L(0); PG8_BAR; PG8_MMA(1, 0, At, B0); PG8_MMA(1, 1, At, B1); PG8_BAR; PG8_SCHED;
.LBB0_555:
	s_add_u32 s6, s4, 0x100
	s_addc_u32 s7, s5, 0
	s_cmp_eq_u32 s51, 28
	s_cselect_b32 s12, s35, s6
	s_cselect_b32 s13, s34, s7
	s_cselect_b32 s10, s39, s40
	s_cselect_b32 s11, s38, s49
	s_add_u32 s8, s12, 0x80
	s_addc_u32 s9, s13, 0
	s_add_i32 s56, 0, 0x10000
	s_add_i32 s57, 0, 0x14000
	ds_read_b128 v[26:29], v244
	ds_read_b128 v[30:33], v244 offset:1024
	ds_read_b128 v[98:101], v244 offset:2048
	ds_read_b128 v[102:105], v244 offset:3072
	ds_read_b128 v[146:149], v244 offset:16384
	ds_read_b128 v[150:153], v244 offset:17408
	ds_read_b128 v[154:157], v244 offset:18432
	ds_read_b128 v[158:161], v244 offset:19456
	s_add_u32 s4, s4, 0x80080
	s_addc_u32 s5, s5, 0
	ds_read_b128 v[178:181], v210
	ds_read_b128 v[182:185], v210 offset:1024
	ds_read_b128 v[186:189], v210 offset:2048
	ds_read_b128 v[190:193], v210 offset:3072
	ds_read_b128 v[194:197], v210 offset:4096
	ds_read_b128 v[198:201], v210 offset:5120
	ds_read_b128 v[202:205], v210 offset:6144
	ds_read_b128 v[212:215], v210 offset:7168
	s_add_i32 m0, s18, 0xc000
	s_nop 0
	global_load_lds_dwordx4 v1, s[4:5]
	s_add_i32 m0, s18, 0xe000
	s_nop 0
	global_load_lds_dwordx4 v164, s[4:5]
	s_waitcnt vmcnt(8)
	s_waitcnt lgkmcnt(0)
	s_barrier
	s_setprio 1
	s_waitcnt lgkmcnt(0)
	v_mfma_f32_16x16x32_bf16 v[142:145], v[26:29], v[178:181], v[142:145]
	v_mfma_f32_16x16x32_bf16 v[142:145], v[30:33], v[182:185], v[142:145]
	v_mfma_f32_16x16x32_bf16 v[134:137], v[26:29], v[186:189], v[134:137]
	v_mfma_f32_16x16x32_bf16 v[134:137], v[30:33], v[190:193], v[134:137]
	v_mfma_f32_16x16x32_bf16 v[126:129], v[26:29], v[194:197], v[126:129]
	v_mfma_f32_16x16x32_bf16 v[126:129], v[30:33], v[198:201], v[126:129]
	v_mfma_f32_16x16x32_bf16 v[118:121], v[26:29], v[202:205], v[118:121]
	v_mfma_f32_16x16x32_bf16 v[118:121], v[30:33], v[212:215], v[118:121]
	v_mfma_f32_16x16x32_bf16 v[138:141], v[98:101], v[178:181], v[138:141]
	v_mfma_f32_16x16x32_bf16 v[138:141], v[102:105], v[182:185], v[138:141]
	v_mfma_f32_16x16x32_bf16 v[130:133], v[98:101], v[186:189], v[130:133]
	v_mfma_f32_16x16x32_bf16 v[130:133], v[102:105], v[190:193], v[130:133]
	v_mfma_f32_16x16x32_bf16 v[122:125], v[98:101], v[194:197], v[122:125]
	v_mfma_f32_16x16x32_bf16 v[122:125], v[102:105], v[198:201], v[122:125]
	v_mfma_f32_16x16x32_bf16 v[114:117], v[98:101], v[202:205], v[114:117]
	v_mfma_f32_16x16x32_bf16 v[114:117], v[102:105], v[212:215], v[114:117]
	s_setprio 0
	s_setprio 1
	v_mfma_f32_16x16x32_bf16 v[70:73], v[146:149], v[178:181], v[70:73]
	v_mfma_f32_16x16x32_bf16 v[70:73], v[150:153], v[182:185], v[70:73]
	v_mfma_f32_16x16x32_bf16 v[62:65], v[146:149], v[186:189], v[62:65]
	v_mfma_f32_16x16x32_bf16 v[62:65], v[150:153], v[190:193], v[62:65]
	v_mfma_f32_16x16x32_bf16 v[54:57], v[146:149], v[194:197], v[54:57]
	v_mfma_f32_16x16x32_bf16 v[54:57], v[150:153], v[198:201], v[54:57]
	v_mfma_f32_16x16x32_bf16 v[46:49], v[146:149], v[202:205], v[46:49]
	v_mfma_f32_16x16x32_bf16 v[46:49], v[150:153], v[212:215], v[46:49]
	v_mfma_f32_16x16x32_bf16 v[66:69], v[154:157], v[178:181], v[66:69]
	v_mfma_f32_16x16x32_bf16 v[66:69], v[158:161], v[182:185], v[66:69]
	v_mfma_f32_16x16x32_bf16 v[58:61], v[154:157], v[186:189], v[58:61]
	v_mfma_f32_16x16x32_bf16 v[58:61], v[158:161], v[190:193], v[58:61]
	v_mfma_f32_16x16x32_bf16 v[50:53], v[154:157], v[194:197], v[50:53]
	v_mfma_f32_16x16x32_bf16 v[50:53], v[158:161], v[198:201], v[50:53]
	v_mfma_f32_16x16x32_bf16 v[42:45], v[154:157], v[202:205], v[42:45]
	v_mfma_f32_16x16x32_bf16 v[42:45], v[158:161], v[212:215], v[42:45]
	s_setprio 0
	s_barrier
	s_mov_b64 s[4:5], s[10:11]
	s_add_i32 s56, s56, s17
	ds_read_b128 v[178:181], v210 offset:16384
	ds_read_b128 v[182:185], v210 offset:17408
	ds_read_b128 v[186:189], v210 offset:18432
	ds_read_b128 v[190:193], v210 offset:19456
	ds_read_b128 v[194:197], v210 offset:20480
	ds_read_b128 v[198:201], v210 offset:21504
	ds_read_b128 v[202:205], v210 offset:22528
	ds_read_b128 v[212:215], v210 offset:23552
	s_mov_b32 m0, s56
	s_nop 0
	global_load_lds_dwordx4 v162, s[4:5]
	s_add_i32 m0, s56, 0x2000
	s_nop 0
	global_load_lds_dwordx4 v206, s[4:5]
	s_add_u32 s4, s10, 0x80000
	s_addc_u32 s5, s11, 0
	s_add_i32 s56, s57, s17
	s_mov_b32 m0, s56
	s_nop 0
	global_load_lds_dwordx4 v162, s[4:5]
	s_add_i32 m0, s56, 0x2000
	s_nop 0
	global_load_lds_dwordx4 v206, s[4:5]
	s_mov_b64 s[4:5], s[12:13]
	s_mov_b32 m0, s18
	s_nop 0
	global_load_lds_dwordx4 v1, s[4:5]
	s_mov_b32 m0, s19
	s_nop 0
	global_load_lds_dwordx4 v164, s[4:5]
	s_waitcnt vmcnt(8)
	s_waitcnt lgkmcnt(0)
	s_barrier
; #define PG8_STAGE(bufoff, gbase, voff) do { const char* gb_ = (const char*)(gbase); asm volatile("" : "+s"(gb_)); _Pragma("unroll") for (int _i = 0; _i < 2; ++_i) { unsigned vo_ = (voff)[_i]; asm volatile("" : "+v"(vo_));        \
;         __builtin_amdgcn_global_load_lds((const unsigned*)(gb_ + vo_), (PG8_LAS unsigned*)(lds + (bufoff) + ldsw + _i * 8192), 16, 0, 0); } } while (0)
; #define PG8_LDA(dst, b, h) do { _Pragma("unroll") for (int m = 0; m < 4; ++m) _Pragma("unroll") for (int k = 0; k < 2; ++k) dst[m][k] = *(const PG8_LAS bf16x8*)(lds + PG8_SA(b, h) + aoff + m * 2048 + k * 1024); } while (0)
; #define PG8_LDB(dst, b, h) do { _Pragma("unroll") for (int n = 0; n < 2; ++n) _Pragma("unroll") for (int k = 0; k < 2; ++k) dst[n][k] = *(const PG8_LAS bf16x8*)(lds + PG8_SB(b, h) + boff + n * 2048 + k * 1024); } while (0)
; #define PG8_MMA(ai, bj, At, Bt) do { __builtin_amdgcn_s_setprio(1); _Pragma("unroll") for (int m = 0; m < 4; ++m) _Pragma("unroll") for (int n = 0; n < 2; ++n) _Pragma("unroll") for (int k = 0; k < 2; ++k) \
;         acc[ai][bj][m][n] = __builtin_amdgcn_mfma_f32_16x16x32_bf16(Bt[n][k], At[m][k], acc[ai][bj][m][n], 0, 0, 0); __builtin_amdgcn_s_setprio(0); } while (0)
; #define PG8_WAIT_V(n) asm volatile("s_waitcnt vmcnt(" #n ")" ::: "memory")
; #define PG8_WAIT_L(n) asm volatile("s_waitcnt lgkmcnt(" #n ")" ::: "memory")
; #define PG8_BAR __builtin_amdgcn_s_barrier()
; #define PG8_SCHED __builtin_amdgcn_sched_barrier(0)
; template <class Epi, class Sched, bool ALIGN_EPI = false, bool SP2 = false>
; __device__ __forceinline__ void gemm_phase(PG8_LAS unsigned char* lds, const Gemm g, const Sched& S, const Epi& E) {
;     ...
;             PG8_WAIT_V(8); PG8_WAIT_L(0); PG8_BAR; PG8_MMA(1, 0, At, B0); PG8_MMA(1, 1, At, B1); PG8_BAR; PG8_SCHED;
;             PG8_LDB(B0, 1, 0); PG8_LDB(B1, 1, 1); PG8_SCHED; PG8_LDA(At, 1, 0); PG8_STAGE(PG8_SA(0, 1), a2 + hstep, voffA);
;             PG8_WAIT_V(8); PG8_WAIT_L(0); PG8_BAR; PG8_MMA(0, 0, At, B0); PG8_MMA(0, 1, At, B1); PG8_BAR; PG8_SCHED;
;             PG8_LDA(At, 1, 1); PG8_STAGE(PG8_SB(1, 0), b3, voffB); PG8_STAGE(PG8_SB(1, 1), b3 + hstep, voffB); PG8_STAGE(PG8_SA(1, 0), a3, voffA);
	s_setprio 1
	s_waitcnt lgkmcnt(0)
	v_mfma_f32_16x16x32_bf16 v[110:113], v[26:29], v[178:181], v[110:113]
	v_mfma_f32_16x16x32_bf16 v[110:113], v[30:33], v[182:185], v[110:113]
	v_mfma_f32_16x16x32_bf16 v[94:97], v[26:29], v[186:189], v[94:97]
	v_mfma_f32_16x16x32_bf16 v[94:97], v[30:33], v[190:193], v[94:97]
	v_mfma_f32_16x16x32_bf16 v[86:89], v[26:29], v[194:197], v[86:89]
	v_mfma_f32_16x16x32_bf16 v[86:89], v[30:33], v[198:201], v[86:89]
	v_mfma_f32_16x16x32_bf16 v[26:29], v[26:29], v[202:205], v[78:81]
	v_mfma_f32_16x16x32_bf16 v[26:29], v[30:33], v[212:215], v[26:29]
	v_mfma_f32_16x16x32_bf16 v[106:109], v[98:101], v[178:181], v[106:109]
	v_mfma_f32_16x16x32_bf16 v[106:109], v[102:105], v[182:185], v[106:109]
	v_mfma_f32_16x16x32_bf16 v[90:93], v[98:101], v[186:189], v[90:93]
	v_mfma_f32_16x16x32_bf16 v[90:93], v[102:105], v[190:193], v[90:93]
	v_mfma_f32_16x16x32_bf16 v[82:85], v[98:101], v[194:197], v[82:85]
	v_mfma_f32_16x16x32_bf16 v[82:85], v[102:105], v[198:201], v[82:85]
	v_mfma_f32_16x16x32_bf16 v[30:33], v[98:101], v[202:205], v[74:77]
	v_mfma_f32_16x16x32_bf16 v[30:33], v[102:105], v[212:215], v[30:33]
	s_setprio 0
	s_setprio 1
	v_mfma_f32_16x16x32_bf16 v[38:41], v[146:149], v[178:181], v[38:41]
	v_mfma_f32_16x16x32_bf16 v[38:41], v[150:153], v[182:185], v[38:41]
	v_mfma_f32_16x16x32_bf16 v[22:25], v[146:149], v[186:189], v[22:25]
	v_mfma_f32_16x16x32_bf16 v[22:25], v[150:153], v[190:193], v[22:25]
	v_mfma_f32_16x16x32_bf16 v[14:17], v[146:149], v[194:197], v[14:17]
	v_mfma_f32_16x16x32_bf16 v[14:17], v[150:153], v[198:201], v[14:17]
	v_mfma_f32_16x16x32_bf16 v[6:9], v[146:149], v[202:205], v[6:9]
	v_mfma_f32_16x16x32_bf16 v[6:9], v[150:153], v[212:215], v[6:9]
	v_mfma_f32_16x16x32_bf16 v[34:37], v[154:157], v[178:181], v[34:37]
	v_mfma_f32_16x16x32_bf16 v[34:37], v[158:161], v[182:185], v[34:37]
	v_mfma_f32_16x16x32_bf16 v[18:21], v[154:157], v[186:189], v[18:21]
	v_mfma_f32_16x16x32_bf16 v[18:21], v[158:161], v[190:193], v[18:21]
	v_mfma_f32_16x16x32_bf16 v[10:13], v[154:157], v[194:197], v[10:13]
	v_mfma_f32_16x16x32_bf16 v[10:13], v[158:161], v[198:201], v[10:13]
	v_mfma_f32_16x16x32_bf16 v[2:5], v[154:157], v[202:205], v[2:5]
	v_mfma_f32_16x16x32_bf16 v[2:5], v[158:161], v[212:215], v[2:5]
	s_setprio 0
	s_barrier
	s_add_i32 s56, 0, 0x18000
	s_add_i32 s57, 0, 0x1c000
	ds_read_b128 v[74:77], v244 offset:32768
	ds_read_b128 v[78:81], v244 offset:33792
	ds_read_b128 v[98:101], v244 offset:34816
	ds_read_b128 v[102:105], v244 offset:35840
	ds_read_b128 v[146:149], v244 offset:49152
	ds_read_b128 v[150:153], v244 offset:50176
	ds_read_b128 v[154:157], v244 offset:51200
	ds_read_b128 v[158:161], v244 offset:52224
	s_add_u32 s4, s12, 0x80000
	s_addc_u32 s5, s13, 0
	s_mov_b32 m0, s20
	ds_read_b128 v[178:181], v210 offset:32768
	ds_read_b128 v[182:185], v210 offset:33792
	ds_read_b128 v[186:189], v210 offset:34816
	ds_read_b128 v[190:193], v210 offset:35840
	ds_read_b128 v[194:197], v210 offset:36864
	ds_read_b128 v[198:201], v210 offset:37888
	ds_read_b128 v[202:205], v210 offset:38912
	ds_read_b128 v[212:215], v210 offset:39936
	s_nop 0
	global_load_lds_dwordx4 v1, s[4:5]
	s_mov_b32 m0, s21
	s_nop 0
	global_load_lds_dwordx4 v164, s[4:5]
	s_waitcnt vmcnt(8)
	s_waitcnt lgkmcnt(0)
	s_barrier
	s_setprio 1
	s_waitcnt lgkmcnt(0)
	v_mfma_f32_16x16x32_bf16 v[142:145], v[74:77], v[178:181], v[142:145]
	v_mfma_f32_16x16x32_bf16 v[142:145], v[78:81], v[182:185], v[142:145]
	v_mfma_f32_16x16x32_bf16 v[134:137], v[74:77], v[186:189], v[134:137]
	v_mfma_f32_16x16x32_bf16 v[134:137], v[78:81], v[190:193], v[134:137]
	v_mfma_f32_16x16x32_bf16 v[126:129], v[74:77], v[194:197], v[126:129]
	v_mfma_f32_16x16x32_bf16 v[126:129], v[78:81], v[198:201], v[126:129]
	v_mfma_f32_16x16x32_bf16 v[118:121], v[74:77], v[202:205], v[118:121]
	v_mfma_f32_16x16x32_bf16 v[118:121], v[78:81], v[212:215], v[118:121]
	v_mfma_f32_16x16x32_bf16 v[138:141], v[98:101], v[178:181], v[138:141]
	v_mfma_f32_16x16x32_bf16 v[138:141], v[102:105], v[182:185], v[138:141]
	v_mfma_f32_16x16x32_bf16 v[130:133], v[98:101], v[186:189], v[130:133]
	v_mfma_f32_16x16x32_bf16 v[130:133], v[102:105], v[190:193], v[130:133]
	v_mfma_f32_16x16x32_bf16 v[122:125], v[98:101], v[194:197], v[122:125]
	v_mfma_f32_16x16x32_bf16 v[122:125], v[102:105], v[198:201], v[122:125]
	v_mfma_f32_16x16x32_bf16 v[114:117], v[98:101], v[202:205], v[114:117]
	v_mfma_f32_16x16x32_bf16 v[114:117], v[102:105], v[212:215], v[114:117]
	s_setprio 0
	s_setprio 1
	v_mfma_f32_16x16x32_bf16 v[70:73], v[146:149], v[178:181], v[70:73]
	v_mfma_f32_16x16x32_bf16 v[70:73], v[150:153], v[182:185], v[70:73]
	v_mfma_f32_16x16x32_bf16 v[62:65], v[146:149], v[186:189], v[62:65]
	v_mfma_f32_16x16x32_bf16 v[62:65], v[150:153], v[190:193], v[62:65]
	v_mfma_f32_16x16x32_bf16 v[54:57], v[146:149], v[194:197], v[54:57]
	v_mfma_f32_16x16x32_bf16 v[54:57], v[150:153], v[198:201], v[54:57]
	v_mfma_f32_16x16x32_bf16 v[46:49], v[146:149], v[202:205], v[46:49]
	v_mfma_f32_16x16x32_bf16 v[46:49], v[150:153], v[212:215], v[46:49]
	v_mfma_f32_16x16x32_bf16 v[66:69], v[154:157], v[178:181], v[66:69]
	v_mfma_f32_16x16x32_bf16 v[66:69], v[158:161], v[182:185], v[66:69]
	v_mfma_f32_16x16x32_bf16 v[58:61], v[154:157], v[186:189], v[58:61]
	v_mfma_f32_16x16x32_bf16 v[58:61], v[158:161], v[190:193], v[58:61]
	v_mfma_f32_16x16x32_bf16 v[50:53], v[154:157], v[194:197], v[50:53]
	v_mfma_f32_16x16x32_bf16 v[50:53], v[158:161], v[198:201], v[50:53]
	v_mfma_f32_16x16x32_bf16 v[42:45], v[154:157], v[202:205], v[42:45]
	v_mfma_f32_16x16x32_bf16 v[42:45], v[158:161], v[212:215], v[42:45]
	s_setprio 0
	s_barrier
; #define PG8_STAGE(bufoff, gbase, voff) do { const char* gb_ = (const char*)(gbase); asm volatile("" : "+s"(gb_)); _Pragma("unroll") for (int _i = 0; _i < 2; ++_i) { unsigned vo_ = (voff)[_i]; asm volatile("" : "+v"(vo_));        \
;         __builtin_amdgcn_global_load_lds((const unsigned*)(gb_ + vo_), (PG8_LAS unsigned*)(lds + (bufoff) + ldsw + _i * 8192), 16, 0, 0); } } while (0)
; #define PG8_LDA(dst, b, h) do { _Pragma("unroll") for (int m = 0; m < 4; ++m) _Pragma("unroll") for (int k = 0; k < 2; ++k) dst[m][k] = *(const PG8_LAS bf16x8*)(lds + PG8_SA(b, h) + aoff + m * 2048 + k * 1024); } while (0)
; #define PG8_MMA(ai, bj, At, Bt) do { __builtin_amdgcn_s_setprio(1); _Pragma("unroll") for (int m = 0; m < 4; ++m) _Pragma("unroll") for (int n = 0; n < 2; ++n) _Pragma("unroll") for (int k = 0; k < 2; ++k) \
;         acc[ai][bj][m][n] = __builtin_amdgcn_mfma_f32_16x16x32_bf16(Bt[n][k], At[m][k], acc[ai][bj][m][n], 0, 0, 0); __builtin_amdgcn_s_setprio(0); } while (0)
; #define PG8_WAIT_V(n) asm volatile("s_waitcnt vmcnt(" #n ")" ::: "memory")
; #define PG8_WAIT_L(n) asm volatile("s_waitcnt lgkmcnt(" #n ")" ::: "memory")
; #define PG8_BAR __builtin_amdgcn_s_barrier()
; #define PG8_SCHED __builtin_amdgcn_sched_barrier(0)
; template <class Epi, class Sched, bool ALIGN_EPI = false, bool SP2 = false>
; __device__ __forceinline__ void gemm_phase(PG8_LAS unsigned char* lds, const Gemm g, const Sched& S, const Epi& E) {
;     ...
;             PG8_LDA(At, 1, 1); PG8_STAGE(PG8_SB(1, 0), b3, voffB); PG8_STAGE(PG8_SB(1, 1), b3 + hstep, voffB); PG8_STAGE(PG8_SA(1, 0), a3, voffA);
;             PG8_WAIT_V(8); PG8_WAIT_L(0); PG8_BAR; PG8_MMA(1, 0, At, B0); PG8_MMA(1, 1, At, B1); PG8_BAR; PG8_SCHED;
;     ...
;         if constexpr (ALIGN_EPI) { if (wr == 0) PG8_BAR; }
	s_add_u32 s4, s10, 0x80
	s_addc_u32 s5, s11, 0
	s_add_i32 s12, s56, s17
	ds_read_b128 v[178:181], v210 offset:49152
	ds_read_b128 v[182:185], v210 offset:50176
	ds_read_b128 v[186:189], v210 offset:51200
	ds_read_b128 v[190:193], v210 offset:52224
	ds_read_b128 v[194:197], v210 offset:53248
	ds_read_b128 v[198:201], v210 offset:54272
	ds_read_b128 v[202:205], v210 offset:55296
	ds_read_b128 v[212:215], v210 offset:56320
	s_mov_b32 m0, s12
	s_nop 0
	global_load_lds_dwordx4 v162, s[4:5]
	s_add_i32 m0, s12, 0x2000
	s_nop 0
	global_load_lds_dwordx4 v206, s[4:5]
	s_add_u32 s4, s10, 0x80080
	s_addc_u32 s5, s11, 0
	s_add_i32 s10, s57, s17
	s_mov_b32 m0, s10
	s_nop 0
	global_load_lds_dwordx4 v162, s[4:5]
	s_add_i32 m0, s10, 0x2000
	s_nop 0
	global_load_lds_dwordx4 v206, s[4:5]
	s_mov_b32 m0, s26
	s_nop 0
	global_load_lds_dwordx4 v1, s[8:9]
	s_mov_b32 m0, s27
	s_nop 0
	global_load_lds_dwordx4 v164, s[8:9]
	s_waitcnt vmcnt(8)
	s_waitcnt lgkmcnt(0)
	s_barrier
	s_setprio 1
	s_waitcnt lgkmcnt(0)
	v_mfma_f32_16x16x32_bf16 v[110:113], v[74:77], v[178:181], v[110:113]
	v_mfma_f32_16x16x32_bf16 v[110:113], v[78:81], v[182:185], v[110:113]
	v_mfma_f32_16x16x32_bf16 v[94:97], v[74:77], v[186:189], v[94:97]
	v_mfma_f32_16x16x32_bf16 v[94:97], v[78:81], v[190:193], v[94:97]
	v_mfma_f32_16x16x32_bf16 v[86:89], v[74:77], v[194:197], v[86:89]
	v_mfma_f32_16x16x32_bf16 v[86:89], v[78:81], v[198:201], v[86:89]
	v_mfma_f32_16x16x32_bf16 v[26:29], v[74:77], v[202:205], v[26:29]
	v_mfma_f32_16x16x32_bf16 v[78:81], v[78:81], v[212:215], v[26:29]
	v_mfma_f32_16x16x32_bf16 v[106:109], v[98:101], v[178:181], v[106:109]
	v_mfma_f32_16x16x32_bf16 v[106:109], v[102:105], v[182:185], v[106:109]
	v_mfma_f32_16x16x32_bf16 v[90:93], v[98:101], v[186:189], v[90:93]
	v_mfma_f32_16x16x32_bf16 v[90:93], v[102:105], v[190:193], v[90:93]
	v_mfma_f32_16x16x32_bf16 v[82:85], v[98:101], v[194:197], v[82:85]
	v_mfma_f32_16x16x32_bf16 v[82:85], v[102:105], v[198:201], v[82:85]
	v_mfma_f32_16x16x32_bf16 v[26:29], v[98:101], v[202:205], v[30:33]
	v_mfma_f32_16x16x32_bf16 v[74:77], v[102:105], v[212:215], v[26:29]
	s_setprio 0
	s_setprio 1
	v_mfma_f32_16x16x32_bf16 v[26:29], v[146:149], v[178:181], v[38:41]
	v_mfma_f32_16x16x32_bf16 v[38:41], v[150:153], v[182:185], v[26:29]
	v_mfma_f32_16x16x32_bf16 v[22:25], v[146:149], v[186:189], v[22:25]
	v_mfma_f32_16x16x32_bf16 v[22:25], v[150:153], v[190:193], v[22:25]
	v_mfma_f32_16x16x32_bf16 v[14:17], v[146:149], v[194:197], v[14:17]
	v_mfma_f32_16x16x32_bf16 v[14:17], v[150:153], v[198:201], v[14:17]
	v_mfma_f32_16x16x32_bf16 v[6:9], v[146:149], v[202:205], v[6:9]
	v_mfma_f32_16x16x32_bf16 v[6:9], v[150:153], v[212:215], v[6:9]
	v_mfma_f32_16x16x32_bf16 v[26:29], v[154:157], v[178:181], v[34:37]
	v_mfma_f32_16x16x32_bf16 v[34:37], v[158:161], v[182:185], v[26:29]
	v_mfma_f32_16x16x32_bf16 v[18:21], v[154:157], v[186:189], v[18:21]
	v_mfma_f32_16x16x32_bf16 v[18:21], v[158:161], v[190:193], v[18:21]
	v_mfma_f32_16x16x32_bf16 v[10:13], v[154:157], v[194:197], v[10:13]
	v_mfma_f32_16x16x32_bf16 v[10:13], v[158:161], v[198:201], v[10:13]
	v_mfma_f32_16x16x32_bf16 v[2:5], v[154:157], v[202:205], v[2:5]
	v_mfma_f32_16x16x32_bf16 v[2:5], v[158:161], v[212:215], v[2:5]
	s_setprio 0
	s_barrier
	s_add_i32 s51, s51, 2
	s_add_u32 s40, s40, 0x100
	s_addc_u32 s49, s49, 0
	s_cmp_gt_u32 s51, 29
	s_mov_b64 s[4:5], s[6:7]
	s_cbranch_scc0 .LBB0_555
	s_cmp_lg_u32 s100, 0
	s_cbranch_scc1 .Lal_1
	s_barrier

; #define PG8_BAR __builtin_amdgcn_s_barrier()
; template <class Epi, class Sched, bool ALIGN_EPI = false, bool SP2 = false>
; __device__ __forceinline__ void gemm_phase(PG8_LAS unsigned char* lds, const Gemm g, const Sched& S, const Epi& E) {
;     ...
;     for (;;) {
;         const bool has_next = S.next(ui + 1, nxt);
;         const char* nA = has_next ? (const char*)g.A + (size_t)nxt.pm * tstep : cA; const char* nB = has_next ? (const char*)g.Bt + (size_t)nxt.pn * tstep : cB;
;     ...
;         if constexpr (ALIGN_EPI) { if (wr == 1) PG8_BAR; }
.LBB0_695:
	s_and_b64 vcc, exec, s[0:1]
	s_mov_b32 s30, s27
	s_mov_b32 s29, s28
	s_mov_b64 s[6:7], s[42:43]
	s_mov_b64 s[4:5], s[52:53]
	s_cbranch_vccnz .LBB0_760
	s_cmp_eq_u32 s100, 0
	s_cbranch_scc1 .Lal_3
	s_barrier

; #define PG8_STAGE(bufoff, gbase, voff) do { const char* gb_ = (const char*)(gbase); asm volatile("" : "+s"(gb_)); _Pragma("unroll") for (int _i = 0; _i < 2; ++_i) { unsigned vo_ = (voff)[_i]; asm volatile("" : "+v"(vo_));        \
;         __builtin_amdgcn_global_load_lds((const unsigned*)(gb_ + vo_), (PG8_LAS unsigned*)(lds + (bufoff) + ldsw + _i * 8192), 16, 0, 0); } } while (0)
; #define PG8_LDA(dst, b, h) do { _Pragma("unroll") for (int m = 0; m < 4; ++m) _Pragma("unroll") for (int k = 0; k < 2; ++k) dst[m][k] = *(const PG8_LAS bf16x8*)(lds + PG8_SA(b, h) + aoff + m * 2048 + k * 1024); } while (0)
; #define PG8_LDB(dst, b, h) do { _Pragma("unroll") for (int n = 0; n < 2; ++n) _Pragma("unroll") for (int k = 0; k < 2; ++k) dst[n][k] = *(const PG8_LAS bf16x8*)(lds + PG8_SB(b, h) + boff + n * 2048 + k * 1024); } while (0)
; #define PG8_MMA(ai, bj, At, Bt) do { __builtin_amdgcn_s_setprio(1); _Pragma("unroll") for (int m = 0; m < 4; ++m) _Pragma("unroll") for (int n = 0; n < 2; ++n) _Pragma("unroll") for (int k = 0; k < 2; ++k) \
;         acc[ai][bj][m][n] = __builtin_amdgcn_mfma_f32_16x16x32_bf16(Bt[n][k], At[m][k], acc[ai][bj][m][n], 0, 0, 0); __builtin_amdgcn_s_setprio(0); } while (0)
; #define PG8_WAIT_V(n) asm volatile("s_waitcnt vmcnt(" #n ")" ::: "memory")
; template <class Epi, class Sched, bool ALIGN_EPI = false, bool SP2 = false>
; __device__ __forceinline__ void gemm_phase(PG8_LAS unsigned char* lds, const Gemm g, const Sched& S, const Epi& E) {
;     ...
;             const bool last = (t == nt - 2);
;             const char* a1 = cA + (size_t)(t + 1) * kstep;
;             const char* a2 = last ? nA : cA + (size_t)(t + 2) * kstep; const char* b2 = last ? nB : cB + (size_t)(t + 2) * kstep;
;             const char* a3 = a2 + kstep; const char* b3 = b2 + kstep;
;             if (last && has_next) S.a_ready(nxt);
;             if constexpr (SP2) {
;             PG8_LDB(B0, 0, 0); PG8_LDB(B1, 0, 1); PG8_SCHED; PG8_LDA(At, 0, 0); PG8_STAGE(PG8_SA(1, 1), a1 + hstep, voffA);
;             PG8_WAIT_V(8); PG8_WAIT_L(0); PG8_BAR; PG8_MMA(0, 0, At, B0); PG8_MMA(0, 1, At, B1); PG8_BAR; PG8_SCHED;
;             PG8_LDA(At, 0, 1); PG8_STAGE(PG8_SB(0, 0), b2, voffB); PG8_STAGE(PG8_SB(0, 1), b2 + hstep, voffB); PG8_STAGE(PG8_SA(0, 0), a2, voffA);
;             PG8_WAIT_V(8); PG8_WAIT_L(0); PG8_BAR; PG8_MMA(1, 0, At, B0); PG8_MMA(1, 1, At, B1); PG8_BAR; PG8_SCHED;
.LBB0_707:
	s_add_u32 s2, s4, 0x100
	s_addc_u32 s3, s5, 0
	s_cmpk_eq_i32 s35, 0x54
	s_cselect_b32 s10, s52, s2
	s_cselect_b32 s11, s53, s3
	s_cselect_b32 s8, s42, s31
	s_cselect_b32 s9, s43, s34
	s_add_u32 s6, s10, 0x80
	s_addc_u32 s7, s11, 0
	s_add_i32 s38, 0, 0x10000
	s_add_i32 s39, 0, 0x14000
	ds_read_b128 v[34:37], v244
	ds_read_b128 v[38:41], v244 offset:1024
	ds_read_b128 v[98:101], v244 offset:2048
	ds_read_b128 v[102:105], v244 offset:3072
	ds_read_b128 v[146:149], v244 offset:16384
	ds_read_b128 v[150:153], v244 offset:17408
	ds_read_b128 v[154:157], v244 offset:18432
	ds_read_b128 v[158:161], v244 offset:19456
	s_add_u32 s4, s4, 0x160080
	s_addc_u32 s5, s5, 0
	ds_read_b128 v[178:181], v194
	ds_read_b128 v[182:185], v194 offset:1024
	ds_read_b128 v[186:189], v194 offset:2048
	ds_read_b128 v[196:199], v194 offset:3072
	ds_read_b128 v[200:203], v194 offset:4096
	ds_read_b128 v[204:207], v194 offset:5120
	ds_read_b128 v[208:211], v194 offset:6144
	ds_read_b128 v[212:215], v194 offset:7168
	s_add_i32 m0, s16, 0xc000
	s_nop 0
	global_load_lds_dwordx4 v1, s[4:5]
	s_add_i32 m0, s16, 0xe000
	s_nop 0
	global_load_lds_dwordx4 v164, s[4:5]
	s_waitcnt vmcnt(8)
	s_waitcnt lgkmcnt(0)
	s_barrier
	s_setprio 1
	s_waitcnt lgkmcnt(0)
	v_mfma_f32_16x16x32_bf16 v[142:145], v[34:37], v[178:181], v[142:145]
	v_mfma_f32_16x16x32_bf16 v[142:145], v[38:41], v[182:185], v[142:145]
	v_mfma_f32_16x16x32_bf16 v[134:137], v[34:37], v[186:189], v[134:137]
	v_mfma_f32_16x16x32_bf16 v[134:137], v[38:41], v[196:199], v[134:137]
	v_mfma_f32_16x16x32_bf16 v[126:129], v[34:37], v[200:203], v[126:129]
	v_mfma_f32_16x16x32_bf16 v[126:129], v[38:41], v[204:207], v[126:129]
	v_mfma_f32_16x16x32_bf16 v[118:121], v[34:37], v[208:211], v[118:121]
	v_mfma_f32_16x16x32_bf16 v[118:121], v[38:41], v[212:215], v[118:121]
	v_mfma_f32_16x16x32_bf16 v[138:141], v[98:101], v[178:181], v[138:141]
	v_mfma_f32_16x16x32_bf16 v[138:141], v[102:105], v[182:185], v[138:141]
	v_mfma_f32_16x16x32_bf16 v[130:133], v[98:101], v[186:189], v[130:133]
	v_mfma_f32_16x16x32_bf16 v[130:133], v[102:105], v[196:199], v[130:133]
	v_mfma_f32_16x16x32_bf16 v[122:125], v[98:101], v[200:203], v[122:125]
	v_mfma_f32_16x16x32_bf16 v[122:125], v[102:105], v[204:207], v[122:125]
	v_mfma_f32_16x16x32_bf16 v[114:117], v[98:101], v[208:211], v[114:117]
	v_mfma_f32_16x16x32_bf16 v[114:117], v[102:105], v[212:215], v[114:117]
	s_setprio 0
	s_setprio 1
	v_mfma_f32_16x16x32_bf16 v[70:73], v[146:149], v[178:181], v[70:73]
	v_mfma_f32_16x16x32_bf16 v[70:73], v[150:153], v[182:185], v[70:73]
	v_mfma_f32_16x16x32_bf16 v[62:65], v[146:149], v[186:189], v[62:65]
	v_mfma_f32_16x16x32_bf16 v[62:65], v[150:153], v[196:199], v[62:65]
	v_mfma_f32_16x16x32_bf16 v[54:57], v[146:149], v[200:203], v[54:57]
	v_mfma_f32_16x16x32_bf16 v[54:57], v[150:153], v[204:207], v[54:57]
	v_mfma_f32_16x16x32_bf16 v[46:49], v[146:149], v[208:211], v[46:49]
	v_mfma_f32_16x16x32_bf16 v[46:49], v[150:153], v[212:215], v[46:49]
	v_mfma_f32_16x16x32_bf16 v[66:69], v[154:157], v[178:181], v[66:69]
	v_mfma_f32_16x16x32_bf16 v[66:69], v[158:161], v[182:185], v[66:69]
	v_mfma_f32_16x16x32_bf16 v[58:61], v[154:157], v[186:189], v[58:61]
	v_mfma_f32_16x16x32_bf16 v[58:61], v[158:161], v[196:199], v[58:61]
	v_mfma_f32_16x16x32_bf16 v[50:53], v[154:157], v[200:203], v[50:53]
	v_mfma_f32_16x16x32_bf16 v[50:53], v[158:161], v[204:207], v[50:53]
	v_mfma_f32_16x16x32_bf16 v[42:45], v[154:157], v[208:211], v[42:45]
	v_mfma_f32_16x16x32_bf16 v[42:45], v[158:161], v[212:215], v[42:45]
	s_setprio 0
	s_barrier
	s_mov_b64 s[4:5], s[8:9]
	s_add_i32 s38, s38, s15
	ds_read_b128 v[178:181], v194 offset:16384
	ds_read_b128 v[182:185], v194 offset:17408
	ds_read_b128 v[186:189], v194 offset:18432
	ds_read_b128 v[196:199], v194 offset:19456
	ds_read_b128 v[200:203], v194 offset:20480
	ds_read_b128 v[204:207], v194 offset:21504
	ds_read_b128 v[208:211], v194 offset:22528
	ds_read_b128 v[212:215], v194 offset:23552
	s_mov_b32 m0, s38
	s_nop 0
	global_load_lds_dwordx4 v162, s[4:5]
	s_add_i32 m0, s38, 0x2000
	s_nop 0
	global_load_lds_dwordx4 v190, s[4:5]
	s_add_u32 s4, s8, 0x160000
	s_addc_u32 s5, s9, 0
	s_add_i32 s38, s39, s15
	s_mov_b32 m0, s38
	s_nop 0
	global_load_lds_dwordx4 v162, s[4:5]
	s_add_i32 m0, s38, 0x2000
	s_nop 0
	global_load_lds_dwordx4 v190, s[4:5]
	s_mov_b64 s[4:5], s[10:11]
	s_mov_b32 m0, s16
	s_nop 0
	global_load_lds_dwordx4 v1, s[4:5]
	s_mov_b32 m0, s17
	s_nop 0
	global_load_lds_dwordx4 v164, s[4:5]
	s_waitcnt vmcnt(8)
	s_waitcnt lgkmcnt(0)
	s_barrier
; #define PG8_STAGE(bufoff, gbase, voff) do { const char* gb_ = (const char*)(gbase); asm volatile("" : "+s"(gb_)); _Pragma("unroll") for (int _i = 0; _i < 2; ++_i) { unsigned vo_ = (voff)[_i]; asm volatile("" : "+v"(vo_));        \
;         __builtin_amdgcn_global_load_lds((const unsigned*)(gb_ + vo_), (PG8_LAS unsigned*)(lds + (bufoff) + ldsw + _i * 8192), 16, 0, 0); } } while (0)
; #define PG8_LDA(dst, b, h) do { _Pragma("unroll") for (int m = 0; m < 4; ++m) _Pragma("unroll") for (int k = 0; k < 2; ++k) dst[m][k] = *(const PG8_LAS bf16x8*)(lds + PG8_SA(b, h) + aoff + m * 2048 + k * 1024); } while (0)
; #define PG8_LDB(dst, b, h) do { _Pragma("unroll") for (int n = 0; n < 2; ++n) _Pragma("unroll") for (int k = 0; k < 2; ++k) dst[n][k] = *(const PG8_LAS bf16x8*)(lds + PG8_SB(b, h) + boff + n * 2048 + k * 1024); } while (0)
; #define PG8_MMA(ai, bj, At, Bt) do { __builtin_amdgcn_s_setprio(1); _Pragma("unroll") for (int m = 0; m < 4; ++m) _Pragma("unroll") for (int n = 0; n < 2; ++n) _Pragma("unroll") for (int k = 0; k < 2; ++k) \
;         acc[ai][bj][m][n] = __builtin_amdgcn_mfma_f32_16x16x32_bf16(Bt[n][k], At[m][k], acc[ai][bj][m][n], 0, 0, 0); __builtin_amdgcn_s_setprio(0); } while (0)
; #define PG8_WAIT_V(n) asm volatile("s_waitcnt vmcnt(" #n ")" ::: "memory")
; #define PG8_WAIT_L(n) asm volatile("s_waitcnt lgkmcnt(" #n ")" ::: "memory")
; #define PG8_BAR __builtin_amdgcn_s_barrier()
; #define PG8_SCHED __builtin_amdgcn_sched_barrier(0)
; template <class Epi, class Sched, bool ALIGN_EPI = false, bool SP2 = false>
; __device__ __forceinline__ void gemm_phase(PG8_LAS unsigned char* lds, const Gemm g, const Sched& S, const Epi& E) {
;     ...
;             PG8_WAIT_V(8); PG8_WAIT_L(0); PG8_BAR; PG8_MMA(1, 0, At, B0); PG8_MMA(1, 1, At, B1); PG8_BAR; PG8_SCHED;
;             PG8_LDB(B0, 1, 0); PG8_LDB(B1, 1, 1); PG8_SCHED; PG8_LDA(At, 1, 0); PG8_STAGE(PG8_SA(0, 1), a2 + hstep, voffA);
;             PG8_WAIT_V(8); PG8_WAIT_L(0); PG8_BAR; PG8_MMA(0, 0, At, B0); PG8_MMA(0, 1, At, B1); PG8_BAR; PG8_SCHED;
;             PG8_LDA(At, 1, 1); PG8_STAGE(PG8_SB(1, 0), b3, voffB); PG8_STAGE(PG8_SB(1, 1), b3 + hstep, voffB); PG8_STAGE(PG8_SA(1, 0), a3, voffA);
	s_setprio 1
	s_waitcnt lgkmcnt(0)
	v_mfma_f32_16x16x32_bf16 v[110:113], v[34:37], v[178:181], v[110:113]
	v_mfma_f32_16x16x32_bf16 v[110:113], v[38:41], v[182:185], v[110:113]
	v_mfma_f32_16x16x32_bf16 v[94:97], v[34:37], v[186:189], v[94:97]
	v_mfma_f32_16x16x32_bf16 v[94:97], v[38:41], v[196:199], v[94:97]
	v_mfma_f32_16x16x32_bf16 v[86:89], v[34:37], v[200:203], v[86:89]
	v_mfma_f32_16x16x32_bf16 v[86:89], v[38:41], v[204:207], v[86:89]
	v_mfma_f32_16x16x32_bf16 v[34:37], v[34:37], v[208:211], v[78:81]
	v_mfma_f32_16x16x32_bf16 v[34:37], v[38:41], v[212:215], v[34:37]
	v_mfma_f32_16x16x32_bf16 v[106:109], v[98:101], v[178:181], v[106:109]
	v_mfma_f32_16x16x32_bf16 v[106:109], v[102:105], v[182:185], v[106:109]
	v_mfma_f32_16x16x32_bf16 v[90:93], v[98:101], v[186:189], v[90:93]
	v_mfma_f32_16x16x32_bf16 v[90:93], v[102:105], v[196:199], v[90:93]
	v_mfma_f32_16x16x32_bf16 v[82:85], v[98:101], v[200:203], v[82:85]
	v_mfma_f32_16x16x32_bf16 v[82:85], v[102:105], v[204:207], v[82:85]
	v_mfma_f32_16x16x32_bf16 v[38:41], v[98:101], v[208:211], v[74:77]
	v_mfma_f32_16x16x32_bf16 v[38:41], v[102:105], v[212:215], v[38:41]
	s_setprio 0
	s_setprio 1
	v_mfma_f32_16x16x32_bf16 v[30:33], v[146:149], v[178:181], v[30:33]
	v_mfma_f32_16x16x32_bf16 v[30:33], v[150:153], v[182:185], v[30:33]
	v_mfma_f32_16x16x32_bf16 v[22:25], v[146:149], v[186:189], v[22:25]
	v_mfma_f32_16x16x32_bf16 v[22:25], v[150:153], v[196:199], v[22:25]
	v_mfma_f32_16x16x32_bf16 v[14:17], v[146:149], v[200:203], v[14:17]
	v_mfma_f32_16x16x32_bf16 v[14:17], v[150:153], v[204:207], v[14:17]
	v_mfma_f32_16x16x32_bf16 v[6:9], v[146:149], v[208:211], v[6:9]
	v_mfma_f32_16x16x32_bf16 v[6:9], v[150:153], v[212:215], v[6:9]
	v_mfma_f32_16x16x32_bf16 v[26:29], v[154:157], v[178:181], v[26:29]
	v_mfma_f32_16x16x32_bf16 v[26:29], v[158:161], v[182:185], v[26:29]
	v_mfma_f32_16x16x32_bf16 v[18:21], v[154:157], v[186:189], v[18:21]
	v_mfma_f32_16x16x32_bf16 v[18:21], v[158:161], v[196:199], v[18:21]
	v_mfma_f32_16x16x32_bf16 v[10:13], v[154:157], v[200:203], v[10:13]
	v_mfma_f32_16x16x32_bf16 v[10:13], v[158:161], v[204:207], v[10:13]
	v_mfma_f32_16x16x32_bf16 v[2:5], v[154:157], v[208:211], v[2:5]
	v_mfma_f32_16x16x32_bf16 v[2:5], v[158:161], v[212:215], v[2:5]
	s_setprio 0
	s_barrier
	s_add_i32 s38, 0, 0x18000
	s_add_i32 s39, 0, 0x1c000
	ds_read_b128 v[74:77], v244 offset:32768
	ds_read_b128 v[78:81], v244 offset:33792
	ds_read_b128 v[98:101], v244 offset:34816
	ds_read_b128 v[102:105], v244 offset:35840
	ds_read_b128 v[146:149], v244 offset:49152
	ds_read_b128 v[150:153], v244 offset:50176
	ds_read_b128 v[154:157], v244 offset:51200
	ds_read_b128 v[158:161], v244 offset:52224
	s_add_u32 s4, s10, 0x160000
	s_addc_u32 s5, s11, 0
	s_mov_b32 m0, s18
	ds_read_b128 v[178:181], v194 offset:32768
	ds_read_b128 v[182:185], v194 offset:33792
	ds_read_b128 v[186:189], v194 offset:34816
	ds_read_b128 v[196:199], v194 offset:35840
	ds_read_b128 v[200:203], v194 offset:36864
	ds_read_b128 v[204:207], v194 offset:37888
	ds_read_b128 v[208:211], v194 offset:38912
	ds_read_b128 v[212:215], v194 offset:39936
	s_nop 0
	global_load_lds_dwordx4 v1, s[4:5]
	s_mov_b32 m0, s19
	s_nop 0
	global_load_lds_dwordx4 v164, s[4:5]
	s_waitcnt vmcnt(8)
	s_waitcnt lgkmcnt(0)
	s_barrier
	s_setprio 1
	s_waitcnt lgkmcnt(0)
	v_mfma_f32_16x16x32_bf16 v[142:145], v[74:77], v[178:181], v[142:145]
	v_mfma_f32_16x16x32_bf16 v[142:145], v[78:81], v[182:185], v[142:145]
	v_mfma_f32_16x16x32_bf16 v[134:137], v[74:77], v[186:189], v[134:137]
	v_mfma_f32_16x16x32_bf16 v[134:137], v[78:81], v[196:199], v[134:137]
	v_mfma_f32_16x16x32_bf16 v[126:129], v[74:77], v[200:203], v[126:129]
	v_mfma_f32_16x16x32_bf16 v[126:129], v[78:81], v[204:207], v[126:129]
	v_mfma_f32_16x16x32_bf16 v[118:121], v[74:77], v[208:211], v[118:121]
	v_mfma_f32_16x16x32_bf16 v[118:121], v[78:81], v[212:215], v[118:121]
	v_mfma_f32_16x16x32_bf16 v[138:141], v[98:101], v[178:181], v[138:141]
	v_mfma_f32_16x16x32_bf16 v[138:141], v[102:105], v[182:185], v[138:141]
	v_mfma_f32_16x16x32_bf16 v[130:133], v[98:101], v[186:189], v[130:133]
	v_mfma_f32_16x16x32_bf16 v[130:133], v[102:105], v[196:199], v[130:133]
	v_mfma_f32_16x16x32_bf16 v[122:125], v[98:101], v[200:203], v[122:125]
	v_mfma_f32_16x16x32_bf16 v[122:125], v[102:105], v[204:207], v[122:125]
	v_mfma_f32_16x16x32_bf16 v[114:117], v[98:101], v[208:211], v[114:117]
	v_mfma_f32_16x16x32_bf16 v[114:117], v[102:105], v[212:215], v[114:117]
	s_setprio 0
	s_setprio 1
	v_mfma_f32_16x16x32_bf16 v[70:73], v[146:149], v[178:181], v[70:73]
	v_mfma_f32_16x16x32_bf16 v[70:73], v[150:153], v[182:185], v[70:73]
	v_mfma_f32_16x16x32_bf16 v[62:65], v[146:149], v[186:189], v[62:65]
	v_mfma_f32_16x16x32_bf16 v[62:65], v[150:153], v[196:199], v[62:65]
	v_mfma_f32_16x16x32_bf16 v[54:57], v[146:149], v[200:203], v[54:57]
	v_mfma_f32_16x16x32_bf16 v[54:57], v[150:153], v[204:207], v[54:57]
	v_mfma_f32_16x16x32_bf16 v[46:49], v[146:149], v[208:211], v[46:49]
	v_mfma_f32_16x16x32_bf16 v[46:49], v[150:153], v[212:215], v[46:49]
	v_mfma_f32_16x16x32_bf16 v[66:69], v[154:157], v[178:181], v[66:69]
	v_mfma_f32_16x16x32_bf16 v[66:69], v[158:161], v[182:185], v[66:69]
	v_mfma_f32_16x16x32_bf16 v[58:61], v[154:157], v[186:189], v[58:61]
	v_mfma_f32_16x16x32_bf16 v[58:61], v[158:161], v[196:199], v[58:61]
	v_mfma_f32_16x16x32_bf16 v[50:53], v[154:157], v[200:203], v[50:53]
	v_mfma_f32_16x16x32_bf16 v[50:53], v[158:161], v[204:207], v[50:53]
	v_mfma_f32_16x16x32_bf16 v[42:45], v[154:157], v[208:211], v[42:45]
	v_mfma_f32_16x16x32_bf16 v[42:45], v[158:161], v[212:215], v[42:45]
	s_setprio 0
	s_barrier
; #define PG8_LDA(dst, b, h) do { _Pragma("unroll") for (int m = 0; m < 4; ++m) _Pragma("unroll") for (int k = 0; k < 2; ++k) dst[m][k] = *(const PG8_LAS bf16x8*)(lds + PG8_SA(b, h) + aoff + m * 2048 + k * 1024); } while (0)
;     __device__ __forceinline__ void operator()(const f32x4 (&acc)[2][2][4][2], const Unit& u, int wr, int wc, int fr, int fq) const {
;         const int row0 = u.pm * BM + wr * 64 + fr, col0 = u.pn * BM + wc * 32 + 8 * fq, b = (u.pm * BM) / rows_per_batch;
;         const float* g = gate + (size_t)b * gate_bstride + col0;
;         float ssq[2][4];
; #pragma unroll
;         for (int ai = 0; ai < 2; ++ai)
; #pragma unroll
;             for (int m = 0; m < 4; ++m) ssq[ai][m] = 0.f;
;         f32x4 gv[2][2], Gv[2][2];
; #pragma unroll
;         for (int bj = 0; bj < 2; ++bj) { gv[bj][0] = *(const f32x4*)(g + bj * HALF); gv[bj][1] = *(const f32x4*)(g + bj * HALF + 4); Gv[bj][0] = (f32x4){0.f, 0.f, 0.f, 0.f}; Gv[bj][1] = (f32x4){0.f, 0.f, 0.f, 0.f};
;             if (Hn) { const float* sc = scnext + (size_t)b * gate_bstride + col0 + bj * HALF;
;                 Gv[bj][0] = *(const f32x4*)(gnext + col0 + bj * HALF) * (1.0f + *(const f32x4*)(sc)); Gv[bj][1] = *(const f32x4*)(gnext + col0 + bj * HALF + 4) * (1.0f + *(const f32x4*)(sc + 4)); } }
; #pragma unroll
;         for (int bj = 0; bj < 2; ++bj) {
;             const f32x4 g0 = gv[bj][0], g1 = gv[bj][1], G0 = Gv[bj][0], G1 = Gv[bj][1];
; #pragma unroll
;             for (int ai = 0; ai < 2; ++ai)
; #pragma unroll
;                 for (int m = 0; m < 4; ++m) { const size_t off = (size_t)(row0 + ai * HALF + m * 16) * 2048 + col0 + bj * HALF;
;                     f32x4 x0 = __builtin_nontemporal_load((const f32x4*)(base + off)), x1 = __builtin_nontemporal_load((const f32x4*)(base + off + 4));
;                     if constexpr (HAS_DIN) { const u32x4 dw = __builtin_nontemporal_load((const u32x4*)(dbuf + off));
; template <class Epi, class Sched, bool ALIGN_EPI = false, bool SP2 = false>
; __device__ __forceinline__ void gemm_phase(PG8_LAS unsigned char* lds, const Gemm g, const Sched& S, const Epi& E) {
;     ...
;             PG8_LDA(At, 1, 1); PG8_STAGE(PG8_SB(1, 0), b3, voffB); PG8_STAGE(PG8_SB(1, 1), b3 + hstep, voffB); PG8_STAGE(PG8_SA(1, 0), a3, voffA);
;             PG8_WAIT_V(8); PG8_WAIT_L(0); PG8_BAR; PG8_MMA(1, 0, At, B0); PG8_MMA(1, 1, At, B1); PG8_BAR; PG8_SCHED;
	s_add_u32 s4, s8, 0x80
	s_addc_u32 s5, s9, 0
	s_add_i32 s10, s38, s15
	ds_read_b128 v[178:181], v194 offset:49152
	ds_read_b128 v[182:185], v194 offset:50176
	ds_read_b128 v[186:189], v194 offset:51200
	ds_read_b128 v[196:199], v194 offset:52224
	ds_read_b128 v[200:203], v194 offset:53248
	ds_read_b128 v[204:207], v194 offset:54272
	ds_read_b128 v[208:211], v194 offset:55296
	ds_read_b128 v[212:215], v194 offset:56320
	s_mov_b32 m0, s10
	s_nop 0
	global_load_lds_dwordx4 v162, s[4:5]
	s_add_i32 m0, s10, 0x2000
	s_nop 0
	global_load_lds_dwordx4 v190, s[4:5]
	s_add_u32 s4, s8, 0x160080
	s_addc_u32 s5, s9, 0
	s_add_i32 s8, s39, s15
	s_mov_b32 m0, s8
	s_nop 0
	global_load_lds_dwordx4 v162, s[4:5]
	s_add_i32 m0, s8, 0x2000
	s_nop 0
	global_load_lds_dwordx4 v190, s[4:5]
	s_mov_b32 m0, s24
	s_nop 0
	global_load_lds_dwordx4 v1, s[6:7]
	s_mov_b32 m0, s25
	s_nop 0
	global_load_lds_dwordx4 v164, s[6:7]
	s_waitcnt vmcnt(8)
	s_waitcnt lgkmcnt(0)
	s_barrier
	s_setprio 1
	s_waitcnt lgkmcnt(0)
	v_mfma_f32_16x16x32_bf16 v[110:113], v[74:77], v[178:181], v[110:113]
	v_mfma_f32_16x16x32_bf16 v[110:113], v[78:81], v[182:185], v[110:113]
	v_mfma_f32_16x16x32_bf16 v[94:97], v[74:77], v[186:189], v[94:97]
	v_mfma_f32_16x16x32_bf16 v[94:97], v[78:81], v[196:199], v[94:97]
	v_mfma_f32_16x16x32_bf16 v[86:89], v[74:77], v[200:203], v[86:89]
	v_mfma_f32_16x16x32_bf16 v[86:89], v[78:81], v[204:207], v[86:89]
	v_mfma_f32_16x16x32_bf16 v[34:37], v[74:77], v[208:211], v[34:37]
	v_mfma_f32_16x16x32_bf16 v[78:81], v[78:81], v[212:215], v[34:37]
	v_mfma_f32_16x16x32_bf16 v[106:109], v[98:101], v[178:181], v[106:109]
	v_mfma_f32_16x16x32_bf16 v[106:109], v[102:105], v[182:185], v[106:109]
	v_mfma_f32_16x16x32_bf16 v[90:93], v[98:101], v[186:189], v[90:93]
	v_mfma_f32_16x16x32_bf16 v[90:93], v[102:105], v[196:199], v[90:93]
	v_mfma_f32_16x16x32_bf16 v[82:85], v[98:101], v[200:203], v[82:85]
	v_mfma_f32_16x16x32_bf16 v[82:85], v[102:105], v[204:207], v[82:85]
	v_mfma_f32_16x16x32_bf16 v[34:37], v[98:101], v[208:211], v[38:41]
	v_mfma_f32_16x16x32_bf16 v[74:77], v[102:105], v[212:215], v[34:37]
	s_setprio 0
	s_setprio 1
	v_mfma_f32_16x16x32_bf16 v[30:33], v[146:149], v[178:181], v[30:33]
	v_mfma_f32_16x16x32_bf16 v[30:33], v[150:153], v[182:185], v[30:33]
	v_mfma_f32_16x16x32_bf16 v[22:25], v[146:149], v[186:189], v[22:25]
	v_mfma_f32_16x16x32_bf16 v[22:25], v[150:153], v[196:199], v[22:25]
	v_mfma_f32_16x16x32_bf16 v[14:17], v[146:149], v[200:203], v[14:17]
	v_mfma_f32_16x16x32_bf16 v[14:17], v[150:153], v[204:207], v[14:17]
	v_mfma_f32_16x16x32_bf16 v[6:9], v[146:149], v[208:211], v[6:9]
	v_mfma_f32_16x16x32_bf16 v[6:9], v[150:153], v[212:215], v[6:9]
	v_mfma_f32_16x16x32_bf16 v[26:29], v[154:157], v[178:181], v[26:29]
	v_mfma_f32_16x16x32_bf16 v[26:29], v[158:161], v[182:185], v[26:29]
	v_mfma_f32_16x16x32_bf16 v[18:21], v[154:157], v[186:189], v[18:21]
	v_mfma_f32_16x16x32_bf16 v[18:21], v[158:161], v[196:199], v[18:21]
	v_mfma_f32_16x16x32_bf16 v[10:13], v[154:157], v[200:203], v[10:13]
	v_mfma_f32_16x16x32_bf16 v[10:13], v[158:161], v[204:207], v[10:13]
	v_mfma_f32_16x16x32_bf16 v[2:5], v[154:157], v[208:211], v[2:5]
	v_mfma_f32_16x16x32_bf16 v[2:5], v[158:161], v[212:215], v[2:5]
	s_setprio 0
	s_barrier
	s_add_i32 s35, s35, 2
	s_add_u32 s31, s31, 0x100
	s_addc_u32 s34, s34, 0
	s_cmpk_gt_u32 s35, 0x55
	s_mov_b64 s[4:5], s[2:3]
	s_cbranch_scc0 .LBB0_707
	s_cmp_lg_u32 s100, 0
	s_cbranch_scc1 .Lal_4
	s_barrier
.Lal_4:
	v_lshl_add_u32 v248, s29, 8, v191
	v_lshl_or_b32 v250, s30, 8, v193
	v_lshlrev_b32_e32 v248, 11, v248
	v_add_u32_e32 v248, v248, v250
	v_mov_b32_e32 v249, 0
	v_lshl_add_u64 v[250:251], v[248:249], 1, s[90:91]
	v_lshl_add_u64 v[248:249], v[248:249], 2, s[44:45]
	global_load_dwordx4 v[220:223], v[248:249], off offset:16 nt
	global_load_dwordx4 v[224:227], v[248:249], off nt
	global_load_dwordx4 v[228:231], v[250:251], off nt
	s_mov_b32 s98, 0x20000
	s_mov_b32 s99, 0
	v_lshl_add_u64 v[252:253], v[248:249], 0, s[98:99]
	s_mov_b32 s98, 0x10000
	v_lshl_add_u64 v[254:255], v[250:251], 0, s[98:99]
	global_load_dwordx4 v[232:235], v[252:253], off offset:16 nt
	global_load_dwordx4 v[236:239], v[252:253], off nt
	global_load_dwordx4 v[244:247], v[254:255], off nt
	s_ashr_i32 s2, s29, 31
	s_lshr_b32 s2, s2, 27
	s_add_i32 s2, s29, s2
	s_ashr_i32 s2, s2, 5
	v_lshl_or_b32 v156, s30, 8, v193
	s_mul_i32 s5, s2, 0xc000
	v_ashrrev_i32_e32 v157, 31, v156
	s_mul_hi_i32 s4, s2, 0xc000
	s_add_u32 s2, s20, s5
	s_addc_u32 s3, s21, s4
	v_lshlrev_b64 v[34:35], 2, v[156:157]
	v_lshl_add_u64 v[38:39], s[2:3], 0, v[34:35]
	global_load_dwordx4 v[98:101], v[38:39], off offset:16
	global_load_dwordx4 v[102:105], v[38:39], off
	s_add_u32 s2, s22, s5
	s_addc_u32 s3, s23, s4
	v_lshl_add_u64 v[148:149], s[2:3], 0, v[34:35]
	v_lshl_add_u64 v[146:147], s[48:49], 0, v[34:35]
	v_mov_b32_e32 v158, 0
	v_cndmask_b32_e64 v34, 0, 1, s[46:47]
	v_cmp_ne_u32_e64 s[2:3], 1, v34
	s_andn2_b64 vcc, exec, s[46:47]
	v_mov_b32_e32 v159, v158
	v_mov_b32_e32 v160, v158
	v_mov_b32_e32 v161, v158
	v_mov_b32_e32 v178, v158
	v_mov_b32_e32 v179, v158
	v_mov_b32_e32 v180, v158
	v_mov_b32_e32 v181, v158
	s_cbranch_vccnz .LBB0_710
	global_load_dwordx4 v[34:37], v[148:149], off
	global_load_dwordx4 v[150:153], v[148:149], off offset:16
	global_load_dwordx4 v[158:161], v[146:147], off
	global_load_dwordx4 v[178:181], v[146:147], off offset:16
	s_waitcnt vmcnt(0)
	v_pk_add_f32 v[36:37], v[36:37], 1.0 op_sel_hi:[1,0]
	v_pk_add_f32 v[34:35], v[34:35], 1.0 op_sel_hi:[1,0]
	v_pk_add_f32 v[40:41], v[152:153], 1.0 op_sel_hi:[1,0]
	v_pk_add_f32 v[150:151], v[150:151], 1.0 op_sel_hi:[1,0]
	v_pk_mul_f32 v[160:161], v[160:161], v[36:37]
	v_pk_mul_f32 v[158:159], v[158:159], v[34:35]
	v_pk_mul_f32 v[180:181], v[180:181], v[40:41]
	v_pk_mul_f32 v[178:179], v[178:179], v[150:151]

; __device__ __forceinline__ unsigned cvt_pk_bf16(float lo, float hi) { unsigned r; asm volatile("v_cvt_pk_bf16_f32 %0, %1, %2" : "=v"(r) : "v"(lo), "v"(hi)); return r; }
;     __device__ __forceinline__ void operator()(const f32x4 (&acc)[2][2][4][2], const Unit& u, int wr, int wc, int fr, int fq) const {
;     ...
;                 for (int m = 0; m < 4; ++m) { const size_t off = (size_t)(row0 + ai * HALF + m * 16) * 2048 + col0 + bj * HALF;
;                     f32x4 x0 = __builtin_nontemporal_load((const f32x4*)(base + off)), x1 = __builtin_nontemporal_load((const f32x4*)(base + off + 4));
;                     if constexpr (HAS_DIN) { const u32x4 dw = __builtin_nontemporal_load((const u32x4*)(dbuf + off));
;                         x0 += (f32x4){__builtin_bit_cast(float, dw.x << 16), __builtin_bit_cast(float, dw.x & 0xffff0000u), __builtin_bit_cast(float, dw.y << 16), __builtin_bit_cast(float, dw.y & 0xffff0000u)};
;                         x1 += (f32x4){__builtin_bit_cast(float, dw.z << 16), __builtin_bit_cast(float, dw.z & 0xffff0000u), __builtin_bit_cast(float, dw.w << 16), __builtin_bit_cast(float, dw.w & 0xffff0000u)}; }
;                     f32x4 o0, o1;
;                     if constexpr (OUT_DELTA) { const f32x4 d0 = g0 * acc[ai][bj][m][0], d1 = g1 * acc[ai][bj][m][1];
;                         u32x4 w; w.x = cvt_pk_bf16(d0[0], d0[1]); w.y = cvt_pk_bf16(d0[2], d0[3]); w.z = cvt_pk_bf16(d1[0], d1[1]); w.w = cvt_pk_bf16(d1[2], d1[3]);
;                         *(u32x4*)(dbuf + off) = w;
;                         o0 = x0 + (f32x4){__builtin_bit_cast(float, w.x << 16), __builtin_bit_cast(float, w.x & 0xffff0000u), __builtin_bit_cast(float, w.y << 16), __builtin_bit_cast(float, w.y & 0xffff0000u)};
;                         o1 = x1 + (f32x4){__builtin_bit_cast(float, w.z << 16), __builtin_bit_cast(float, w.z & 0xffff0000u), __builtin_bit_cast(float, w.w << 16), __builtin_bit_cast(float, w.w & 0xffff0000u)}; }
;                     else { o0 = x0 + g0 * acc[ai][bj][m][0]; o1 = x1 + g1 * acc[ai][bj][m][1]; *(f32x4*)(out + off) = o0; *(f32x4*)(out + off + 4) = o1; }
;                     if (Hn) { const f32x4 h0 = o0 * G0, h1 = o1 * G1;
;                         u32x4 w; w.x = cvt_pk_bf16(h0[0], h0[1]); w.y = cvt_pk_bf16(h0[2], h0[3]); w.z = cvt_pk_bf16(h1[0], h1[1]); w.w = cvt_pk_bf16(h1[2], h1[3]);
;                         *(u32x4*)(Hn + off) = w;
.LBB0_713:
	v_lshl_add_u32 v146, s29, 8, v191
	v_ashrrev_i32_e32 v147, 31, v146
	v_lshlrev_b64 v[182:183], 11, v[146:147]
	v_lshl_add_u64 v[188:189], v[182:183], 0, v[156:157]
	v_lshlrev_b64 v[186:187], 2, v[188:189]
	v_lshl_add_u64 v[184:185], s[44:45], 0, v[186:187]
	v_lshl_add_u64 v[204:205], v[188:189], 1, s[90:91]
	v_lshl_add_u64 v[186:187], s[70:71], 0, v[186:187]
	v_mov_b32_e32 v195, 0
	s_and_b64 vcc, exec, s[2:3]
	s_mov_b32 s6, 0xcf800000
	s_waitcnt vmcnt(0)
	v_mov_b32_e32 v196, v220
	v_mov_b32_e32 v197, v221
	v_mov_b32_e32 v198, v222
	v_mov_b32_e32 v199, v223
	v_mov_b32_e32 v200, v224
	v_mov_b32_e32 v201, v225
	v_mov_b32_e32 v202, v226
	v_mov_b32_e32 v203, v227
	v_mov_b32_e32 v204, v228
	v_mov_b32_e32 v205, v229
	v_mov_b32_e32 v206, v230
	v_mov_b32_e32 v207, v231
	s_mov_b32 s98, 0x40000
	s_mov_b32 s99, 0
	v_lshl_add_u64 v[252:253], v[248:249], 0, s[98:99]
	s_mov_b32 s98, 0x20000
	v_lshl_add_u64 v[254:255], v[250:251], 0, s[98:99]
	global_load_dwordx4 v[220:223], v[252:253], off offset:16 nt
	global_load_dwordx4 v[224:227], v[252:253], off nt
	global_load_dwordx4 v[228:231], v[254:255], off nt
	v_lshlrev_b32_e32 v208, 16, v204
	v_and_b32_e32 v209, 0xffff0000, v204
	v_lshlrev_b32_e32 v204, 16, v205
	v_and_b32_e32 v205, 0xffff0000, v205
	v_pk_add_f32 v[202:203], v[202:203], v[204:205]
	v_lshlrev_b32_e32 v204, 16, v206
	v_and_b32_e32 v205, 0xffff0000, v206
	v_lshlrev_b32_e32 v206, 16, v207
	v_and_b32_e32 v207, 0xffff0000, v207
	v_pk_add_f32 v[200:201], v[200:201], v[208:209]
	v_pk_add_f32 v[198:199], v[198:199], v[206:207]
	v_pk_add_f32 v[196:197], v[196:197], v[204:205]
	v_pk_fma_f32 v[144:145], v[144:145], v[104:105], v[202:203]
	v_pk_fma_f32 v[142:143], v[142:143], v[102:103], v[200:201]
	v_pk_fma_f32 v[140:141], v[140:141], v[100:101], v[198:199]
	v_pk_fma_f32 v[138:139], v[138:139], v[98:99], v[196:197]
	v_mov_b32_e32 v196, 0
	global_store_dwordx4 v[186:187], v[142:145], off
	global_store_dwordx4 v[186:187], v[138:141], off offset:16
	s_cbranch_vccnz .LBB0_715
	v_pk_mul_f32 v[198:199], v[160:161], v[144:145]
	v_pk_mul_f32 v[196:197], v[158:159], v[142:143]
	v_lshl_add_u64 v[188:189], v[188:189], 1, s[96:97]
	v_pk_mul_f32 v[200:201], v[180:181], v[140:141]
	v_pk_mul_f32 v[202:203], v[178:179], v[138:139]
	v_cvt_pk_bf16_f32 v196, v196, v197
	v_cvt_pk_bf16_f32 v197, v198, v199
	s_nop 0
	v_cvt_pk_bf16_f32 v198, v202, v203
	v_cvt_pk_bf16_f32 v199, v200, v201
	global_store_dwordx4 v[188:189], v[196:199], off
	v_mov_b32_e32 v189, v138
	v_mov_b32_e32 v138, v143
	v_mov_b32_e32 v143, v140
	v_mov_b32_e32 v140, v145
	v_mov_b32_e32 v188, v142
	v_pk_mul_f32 v[138:139], v[138:139], v[138:139]
	v_mov_b32_e32 v142, v144
	v_pk_mul_f32 v[140:141], v[140:141], v[140:141]
	v_pk_fma_f32 v[138:139], v[188:189], v[188:189], v[138:139]
	v_pk_fma_f32 v[140:141], v[142:143], v[142:143], v[140:141]
	s_nop 0
	v_pk_add_f32 v[138:139], v[138:139], v[140:141]
	s_nop 0
	v_add_f32_e32 v196, v138, v139
.LBB0_715:
	s_nop 0
	v_or_b32_e32 v138, 16, v146
	v_ashrrev_i32_e32 v139, 31, v138
	v_lshlrev_b64 v[138:139], 11, v[138:139]
	v_lshl_add_u64 v[144:145], v[138:139], 0, v[156:157]
	v_lshlrev_b64 v[142:143], 2, v[144:145]
	v_lshl_add_u64 v[140:141], s[44:45], 0, v[142:143]
	v_lshl_add_u64 v[188:189], v[144:145], 1, s[90:91]
	v_lshl_add_u64 v[142:143], s[70:71], 0, v[142:143]
	s_and_b64 vcc, exec, s[2:3]
	s_waitcnt vmcnt(5)
	v_mov_b32_e32 v198, v232
	v_mov_b32_e32 v199, v233
	v_mov_b32_e32 v200, v234
	v_mov_b32_e32 v201, v235
	v_mov_b32_e32 v202, v236
	v_mov_b32_e32 v203, v237
	v_mov_b32_e32 v204, v238
	v_mov_b32_e32 v205, v239
	v_mov_b32_e32 v206, v244
	v_mov_b32_e32 v207, v245
	v_mov_b32_e32 v208, v246
	v_mov_b32_e32 v209, v247
	s_mov_b32 s98, 0x60000
	s_mov_b32 s99, 0
	v_lshl_add_u64 v[252:253], v[248:249], 0, s[98:99]
	s_mov_b32 s98, 0x30000
	v_lshl_add_u64 v[254:255], v[250:251], 0, s[98:99]
	global_load_dwordx4 v[232:235], v[252:253], off offset:16 nt
	global_load_dwordx4 v[236:239], v[252:253], off nt
	global_load_dwordx4 v[244:247], v[254:255], off nt
	v_lshlrev_b32_e32 v188, 16, v206
	v_and_b32_e32 v189, 0xffff0000, v206
	v_lshlrev_b32_e32 v206, 16, v207
	v_and_b32_e32 v207, 0xffff0000, v207
	v_pk_add_f32 v[204:205], v[204:205], v[206:207]
	v_pk_add_f32 v[188:189], v[202:203], v[188:189]
	v_lshlrev_b32_e32 v202, 16, v208
	v_and_b32_e32 v203, 0xffff0000, v208
	v_lshlrev_b32_e32 v206, 16, v209
	v_and_b32_e32 v207, 0xffff0000, v209
	v_pk_add_f32 v[200:201], v[200:201], v[206:207]
	v_pk_add_f32 v[198:199], v[198:199], v[202:203]
	v_pk_fma_f32 v[136:137], v[136:137], v[104:105], v[204:205]
	v_pk_fma_f32 v[134:135], v[134:135], v[102:103], v[188:189]
	v_pk_fma_f32 v[132:133], v[132:133], v[100:101], v[200:201]
	v_pk_fma_f32 v[130:131], v[130:131], v[98:99], v[198:199]
	global_store_dwordx4 v[142:143], v[134:137], off
	global_store_dwordx4 v[142:143], v[130:133], off offset:16
	s_cbranch_vccnz .LBB0_717
	v_pk_mul_f32 v[198:199], v[158:159], v[134:135]
	v_pk_mul_f32 v[200:201], v[178:179], v[130:131]
	v_lshl_add_u64 v[144:145], v[144:145], 1, s[96:97]
	v_pk_mul_f32 v[188:189], v[160:161], v[136:137]
	v_pk_mul_f32 v[202:203], v[180:181], v[132:133]
	v_cvt_pk_bf16_f32 v198, v198, v199
	v_cvt_pk_bf16_f32 v199, v188, v189
	v_cvt_pk_bf16_f32 v200, v200, v201
	s_nop 0
	v_cvt_pk_bf16_f32 v201, v202, v203
	global_store_dwordx4 v[144:145], v[198:201], off
	v_mov_b32_e32 v145, v130
	v_mov_b32_e32 v130, v135
	v_mov_b32_e32 v135, v132
	v_mov_b32_e32 v132, v137
	v_mov_b32_e32 v144, v134
	v_pk_mul_f32 v[130:131], v[130:131], v[130:131]
	v_mov_b32_e32 v134, v136
	v_pk_mul_f32 v[132:133], v[132:133], v[132:133]
	v_pk_fma_f32 v[130:131], v[144:145], v[144:145], v[130:131]
	v_pk_fma_f32 v[132:133], v[134:135], v[134:135], v[132:133]
	s_nop 0
	v_pk_add_f32 v[130:131], v[130:131], v[132:133]
	s_nop 0
	v_add_f32_e32 v195, v130, v131
; __device__ __forceinline__ unsigned cvt_pk_bf16(float lo, float hi) { unsigned r; asm volatile("v_cvt_pk_bf16_f32 %0, %1, %2" : "=v"(r) : "v"(lo), "v"(hi)); return r; }
;     __device__ __forceinline__ void operator()(const f32x4 (&acc)[2][2][4][2], const Unit& u, int wr, int wc, int fr, int fq) const {
;     ...
;                 for (int m = 0; m < 4; ++m) { const size_t off = (size_t)(row0 + ai * HALF + m * 16) * 2048 + col0 + bj * HALF;
;                     f32x4 x0 = __builtin_nontemporal_load((const f32x4*)(base + off)), x1 = __builtin_nontemporal_load((const f32x4*)(base + off + 4));
;                     if constexpr (HAS_DIN) { const u32x4 dw = __builtin_nontemporal_load((const u32x4*)(dbuf + off));
;                         x0 += (f32x4){__builtin_bit_cast(float, dw.x << 16), __builtin_bit_cast(float, dw.x & 0xffff0000u), __builtin_bit_cast(float, dw.y << 16), __builtin_bit_cast(float, dw.y & 0xffff0000u)};
;                         x1 += (f32x4){__builtin_bit_cast(float, dw.z << 16), __builtin_bit_cast(float, dw.z & 0xffff0000u), __builtin_bit_cast(float, dw.w << 16), __builtin_bit_cast(float, dw.w & 0xffff0000u)}; }
;                     f32x4 o0, o1;
;                     if constexpr (OUT_DELTA) { const f32x4 d0 = g0 * acc[ai][bj][m][0], d1 = g1 * acc[ai][bj][m][1];
;                         u32x4 w; w.x = cvt_pk_bf16(d0[0], d0[1]); w.y = cvt_pk_bf16(d0[2], d0[3]); w.z = cvt_pk_bf16(d1[0], d1[1]); w.w = cvt_pk_bf16(d1[2], d1[3]);
;                         *(u32x4*)(dbuf + off) = w;
;                         o0 = x0 + (f32x4){__builtin_bit_cast(float, w.x << 16), __builtin_bit_cast(float, w.x & 0xffff0000u), __builtin_bit_cast(float, w.y << 16), __builtin_bit_cast(float, w.y & 0xffff0000u)};
;                         o1 = x1 + (f32x4){__builtin_bit_cast(float, w.z << 16), __builtin_bit_cast(float, w.z & 0xffff0000u), __builtin_bit_cast(float, w.w << 16), __builtin_bit_cast(float, w.w & 0xffff0000u)}; }
;                     else { o0 = x0 + g0 * acc[ai][bj][m][0]; o1 = x1 + g1 * acc[ai][bj][m][1]; *(f32x4*)(out + off) = o0; *(f32x4*)(out + off + 4) = o1; }
;                     if (Hn) { const f32x4 h0 = o0 * G0, h1 = o1 * G1;
;                         u32x4 w; w.x = cvt_pk_bf16(h0[0], h0[1]); w.y = cvt_pk_bf16(h0[2], h0[3]); w.z = cvt_pk_bf16(h1[0], h1[1]); w.w = cvt_pk_bf16(h1[2], h1[3]);
;                         *(u32x4*)(Hn + off) = w;
.LBB0_717:
	s_nop 0
	v_or_b32_e32 v130, 32, v146
	v_ashrrev_i32_e32 v131, 31, v130
	v_lshlrev_b64 v[130:131], 11, v[130:131]
	v_lshl_add_u64 v[136:137], v[130:131], 0, v[156:157]
	v_lshlrev_b64 v[134:135], 2, v[136:137]
	v_lshl_add_u64 v[132:133], s[44:45], 0, v[134:135]
	v_lshl_add_u64 v[144:145], v[136:137], 1, s[90:91]
	v_lshl_add_u64 v[134:135], s[70:71], 0, v[134:135]
	s_and_b64 vcc, exec, s[2:3]
	s_waitcnt vmcnt(7)
	v_mov_b32_e32 v198, v220
	v_mov_b32_e32 v199, v221
	v_mov_b32_e32 v200, v222
	v_mov_b32_e32 v201, v223
	v_mov_b32_e32 v202, v224
	v_mov_b32_e32 v203, v225
	v_mov_b32_e32 v204, v226
	v_mov_b32_e32 v205, v227
	v_mov_b32_e32 v206, v228
	v_mov_b32_e32 v207, v229
	v_mov_b32_e32 v208, v230
	v_mov_b32_e32 v209, v231
	s_mov_b32 s98, 0x100000
	s_mov_b32 s99, 0
	v_lshl_add_u64 v[252:253], v[248:249], 0, s[98:99]
	s_mov_b32 s98, 0x80000
	v_lshl_add_u64 v[254:255], v[250:251], 0, s[98:99]
	global_load_dwordx4 v[220:223], v[252:253], off offset:16 nt
	global_load_dwordx4 v[224:227], v[252:253], off nt
	global_load_dwordx4 v[228:231], v[254:255], off nt
	v_lshlrev_b32_e32 v144, 16, v206
	v_and_b32_e32 v145, 0xffff0000, v206
	v_lshlrev_b32_e32 v188, 16, v207
	v_and_b32_e32 v189, 0xffff0000, v207
	v_pk_add_f32 v[188:189], v[204:205], v[188:189]
	v_pk_add_f32 v[144:145], v[202:203], v[144:145]
	v_lshlrev_b32_e32 v202, 16, v208
	v_and_b32_e32 v203, 0xffff0000, v208
	v_lshlrev_b32_e32 v204, 16, v209
	v_and_b32_e32 v205, 0xffff0000, v209
	v_pk_add_f32 v[200:201], v[200:201], v[204:205]
	v_pk_add_f32 v[198:199], v[198:199], v[202:203]
	v_pk_fma_f32 v[128:129], v[128:129], v[104:105], v[188:189]
	v_pk_fma_f32 v[126:127], v[126:127], v[102:103], v[144:145]
	v_pk_fma_f32 v[124:125], v[124:125], v[100:101], v[200:201]
	v_pk_fma_f32 v[122:123], v[122:123], v[98:99], v[198:199]
	v_mov_b32_e32 v144, 0
	v_mov_b32_e32 v145, 0
	global_store_dwordx4 v[134:135], v[126:129], off
	global_store_dwordx4 v[134:135], v[122:125], off offset:16
	s_cbranch_vccnz .LBB0_719
	v_pk_mul_f32 v[198:199], v[158:159], v[126:127]
	v_pk_mul_f32 v[200:201], v[178:179], v[122:123]
	v_lshl_add_u64 v[136:137], v[136:137], 1, s[96:97]
	v_pk_mul_f32 v[188:189], v[160:161], v[128:129]
	v_pk_mul_f32 v[202:203], v[180:181], v[124:125]
	v_cvt_pk_bf16_f32 v198, v198, v199
	v_cvt_pk_bf16_f32 v199, v188, v189
	v_cvt_pk_bf16_f32 v200, v200, v201
	s_nop 0
	v_cvt_pk_bf16_f32 v201, v202, v203
	global_store_dwordx4 v[136:137], v[198:201], off
	v_mov_b32_e32 v137, v122
	v_mov_b32_e32 v122, v127
	v_mov_b32_e32 v127, v124
	v_mov_b32_e32 v124, v129
	v_mov_b32_e32 v136, v126
	v_pk_mul_f32 v[122:123], v[122:123], v[122:123]
	v_mov_b32_e32 v126, v128
	v_pk_mul_f32 v[124:125], v[124:125], v[124:125]
	v_pk_fma_f32 v[122:123], v[136:137], v[136:137], v[122:123]
	v_pk_fma_f32 v[124:125], v[126:127], v[126:127], v[124:125]
	s_nop 0
	v_pk_add_f32 v[122:123], v[122:123], v[124:125]
	s_nop 0
	v_add_f32_e32 v145, v122, v123
.LBB0_719:
	s_nop 0
	v_or_b32_e32 v122, 48, v146
	v_ashrrev_i32_e32 v123, 31, v122
	v_lshlrev_b64 v[122:123], 11, v[122:123]
	v_lshl_add_u64 v[128:129], v[122:123], 0, v[156:157]
	v_lshlrev_b64 v[126:127], 2, v[128:129]
	v_lshl_add_u64 v[124:125], s[44:45], 0, v[126:127]
	v_lshl_add_u64 v[136:137], v[128:129], 1, s[90:91]
	v_lshl_add_u64 v[126:127], s[70:71], 0, v[126:127]
	s_and_b64 vcc, exec, s[2:3]
	s_waitcnt vmcnt(7)
	v_mov_b32_e32 v198, v232
	v_mov_b32_e32 v199, v233
	v_mov_b32_e32 v200, v234
	v_mov_b32_e32 v201, v235
	v_mov_b32_e32 v202, v236
	v_mov_b32_e32 v203, v237
	v_mov_b32_e32 v204, v238
	v_mov_b32_e32 v205, v239
	v_mov_b32_e32 v206, v244
	v_mov_b32_e32 v207, v245
	v_mov_b32_e32 v208, v246
	v_mov_b32_e32 v209, v247
	s_mov_b32 s98, 0x120000
	s_mov_b32 s99, 0
	v_lshl_add_u64 v[252:253], v[248:249], 0, s[98:99]
	s_mov_b32 s98, 0x90000
	v_lshl_add_u64 v[254:255], v[250:251], 0, s[98:99]
	global_load_dwordx4 v[232:235], v[252:253], off offset:16 nt
	global_load_dwordx4 v[236:239], v[252:253], off nt
	global_load_dwordx4 v[244:247], v[254:255], off nt
	v_lshlrev_b32_e32 v136, 16, v206
	v_and_b32_e32 v137, 0xffff0000, v206
	v_lshlrev_b32_e32 v188, 16, v207
	v_and_b32_e32 v189, 0xffff0000, v207
	v_pk_add_f32 v[188:189], v[204:205], v[188:189]
	v_pk_add_f32 v[136:137], v[202:203], v[136:137]
	v_lshlrev_b32_e32 v202, 16, v208
	v_and_b32_e32 v203, 0xffff0000, v208
	v_lshlrev_b32_e32 v204, 16, v209
	v_and_b32_e32 v205, 0xffff0000, v209
	v_pk_add_f32 v[200:201], v[200:201], v[204:205]
	v_pk_add_f32 v[198:199], v[198:199], v[202:203]
	v_pk_fma_f32 v[120:121], v[120:121], v[104:105], v[188:189]
	v_pk_fma_f32 v[118:119], v[118:119], v[102:103], v[136:137]
	v_pk_fma_f32 v[116:117], v[116:117], v[100:101], v[200:201]
	v_pk_fma_f32 v[114:115], v[114:115], v[98:99], v[198:199]
	global_store_dwordx4 v[126:127], v[118:121], off
	global_store_dwordx4 v[126:127], v[114:117], off offset:16
	s_cbranch_vccnz .LBB0_721
	v_pk_mul_f32 v[200:201], v[178:179], v[114:115]
	v_lshl_add_u64 v[128:129], v[128:129], 1, s[96:97]
	v_pk_mul_f32 v[136:137], v[160:161], v[120:121]
	v_pk_mul_f32 v[188:189], v[158:159], v[118:119]
	v_pk_mul_f32 v[202:203], v[180:181], v[116:117]
	v_cvt_pk_bf16_f32 v198, v188, v189
	v_cvt_pk_bf16_f32 v199, v136, v137
	v_cvt_pk_bf16_f32 v200, v200, v201
	s_nop 0
	v_cvt_pk_bf16_f32 v201, v202, v203
	global_store_dwordx4 v[128:129], v[198:201], off
	v_mov_b32_e32 v129, v114
	v_mov_b32_e32 v114, v119
	v_mov_b32_e32 v119, v116
	v_mov_b32_e32 v116, v121
	v_mov_b32_e32 v128, v118
	v_pk_mul_f32 v[114:115], v[114:115], v[114:115]
	v_mov_b32_e32 v118, v120
	v_pk_mul_f32 v[116:117], v[116:117], v[116:117]
	v_pk_fma_f32 v[114:115], v[128:129], v[128:129], v[114:115]
	v_pk_fma_f32 v[116:117], v[118:119], v[118:119], v[116:117]
	s_nop 0
	v_pk_add_f32 v[114:115], v[114:115], v[116:117]
	s_nop 0
	v_add_f32_e32 v144, v114, v115
; __device__ __forceinline__ unsigned cvt_pk_bf16(float lo, float hi) { unsigned r; asm volatile("v_cvt_pk_bf16_f32 %0, %1, %2" : "=v"(r) : "v"(lo), "v"(hi)); return r; }
;     __device__ __forceinline__ void operator()(const f32x4 (&acc)[2][2][4][2], const Unit& u, int wr, int wc, int fr, int fq) const {
;     ...
;                 for (int m = 0; m < 4; ++m) { const size_t off = (size_t)(row0 + ai * HALF + m * 16) * 2048 + col0 + bj * HALF;
;                     f32x4 x0 = __builtin_nontemporal_load((const f32x4*)(base + off)), x1 = __builtin_nontemporal_load((const f32x4*)(base + off + 4));
;                     if constexpr (HAS_DIN) { const u32x4 dw = __builtin_nontemporal_load((const u32x4*)(dbuf + off));
;                         x0 += (f32x4){__builtin_bit_cast(float, dw.x << 16), __builtin_bit_cast(float, dw.x & 0xffff0000u), __builtin_bit_cast(float, dw.y << 16), __builtin_bit_cast(float, dw.y & 0xffff0000u)};
;                         x1 += (f32x4){__builtin_bit_cast(float, dw.z << 16), __builtin_bit_cast(float, dw.z & 0xffff0000u), __builtin_bit_cast(float, dw.w << 16), __builtin_bit_cast(float, dw.w & 0xffff0000u)}; }
;                     f32x4 o0, o1;
;                     if constexpr (OUT_DELTA) { const f32x4 d0 = g0 * acc[ai][bj][m][0], d1 = g1 * acc[ai][bj][m][1];
;                         u32x4 w; w.x = cvt_pk_bf16(d0[0], d0[1]); w.y = cvt_pk_bf16(d0[2], d0[3]); w.z = cvt_pk_bf16(d1[0], d1[1]); w.w = cvt_pk_bf16(d1[2], d1[3]);
;                         *(u32x4*)(dbuf + off) = w;
;                         o0 = x0 + (f32x4){__builtin_bit_cast(float, w.x << 16), __builtin_bit_cast(float, w.x & 0xffff0000u), __builtin_bit_cast(float, w.y << 16), __builtin_bit_cast(float, w.y & 0xffff0000u)};
;                         o1 = x1 + (f32x4){__builtin_bit_cast(float, w.z << 16), __builtin_bit_cast(float, w.z & 0xffff0000u), __builtin_bit_cast(float, w.w << 16), __builtin_bit_cast(float, w.w & 0xffff0000u)}; }
;                     else { o0 = x0 + g0 * acc[ai][bj][m][0]; o1 = x1 + g1 * acc[ai][bj][m][1]; *(f32x4*)(out + off) = o0; *(f32x4*)(out + off + 4) = o1; }
;                     if (Hn) { const f32x4 h0 = o0 * G0, h1 = o1 * G1;
;                         u32x4 w; w.x = cvt_pk_bf16(h0[0], h0[1]); w.y = cvt_pk_bf16(h0[2], h0[3]); w.z = cvt_pk_bf16(h1[0], h1[1]); w.w = cvt_pk_bf16(h1[2], h1[3]);
;                         *(u32x4*)(Hn + off) = w;
.LBB0_721:
	s_mov_b64 s[4:5], 0x40000
	v_lshl_add_u64 v[114:115], v[182:183], 0, s[4:5]
	v_lshl_add_u64 v[120:121], v[114:115], 0, v[156:157]
	v_lshlrev_b64 v[118:119], 2, v[120:121]
	v_lshl_add_u64 v[116:117], s[44:45], 0, v[118:119]
	v_lshl_add_u64 v[128:129], v[120:121], 1, s[90:91]
	v_lshl_add_u64 v[118:119], s[70:71], 0, v[118:119]
	s_and_b64 vcc, exec, s[2:3]
	s_waitcnt vmcnt(7)
	v_mov_b32_e32 v198, v220
	v_mov_b32_e32 v199, v221
	v_mov_b32_e32 v200, v222
	v_mov_b32_e32 v201, v223
	v_mov_b32_e32 v202, v224
	v_mov_b32_e32 v203, v225
	v_mov_b32_e32 v204, v226
	v_mov_b32_e32 v205, v227
	v_mov_b32_e32 v206, v228
	v_mov_b32_e32 v207, v229
	v_mov_b32_e32 v208, v230
	v_mov_b32_e32 v209, v231
	s_mov_b32 s98, 0x140000
	s_mov_b32 s99, 0
	v_lshl_add_u64 v[252:253], v[248:249], 0, s[98:99]
	s_mov_b32 s98, 0xa0000
	v_lshl_add_u64 v[254:255], v[250:251], 0, s[98:99]
	global_load_dwordx4 v[220:223], v[252:253], off offset:16 nt
	global_load_dwordx4 v[224:227], v[252:253], off nt
	global_load_dwordx4 v[228:231], v[254:255], off nt
	v_lshlrev_b32_e32 v128, 16, v206
	v_and_b32_e32 v129, 0xffff0000, v206
	v_lshlrev_b32_e32 v136, 16, v207
	v_and_b32_e32 v137, 0xffff0000, v207
	v_pk_add_f32 v[128:129], v[202:203], v[128:129]
	v_lshlrev_b32_e32 v188, 16, v208
	v_and_b32_e32 v189, 0xffff0000, v208
	v_lshlrev_b32_e32 v202, 16, v209
	v_and_b32_e32 v203, 0xffff0000, v209
	v_pk_add_f32 v[136:137], v[204:205], v[136:137]
	v_pk_add_f32 v[200:201], v[200:201], v[202:203]
	v_pk_add_f32 v[188:189], v[198:199], v[188:189]
	v_pk_fma_f32 v[112:113], v[112:113], v[104:105], v[136:137]
	v_pk_fma_f32 v[110:111], v[110:111], v[102:103], v[128:129]
	v_pk_fma_f32 v[108:109], v[108:109], v[100:101], v[200:201]
	v_pk_fma_f32 v[106:107], v[106:107], v[98:99], v[188:189]
	v_mov_b32_e32 v128, 0
	v_mov_b32_e32 v129, 0
	global_store_dwordx4 v[118:119], v[110:113], off
	global_store_dwordx4 v[118:119], v[106:109], off offset:16
	s_cbranch_vccnz .LBB0_723
	v_pk_mul_f32 v[200:201], v[178:179], v[106:107]
	v_lshl_add_u64 v[120:121], v[120:121], 1, s[96:97]
	v_pk_mul_f32 v[136:137], v[160:161], v[112:113]
	v_pk_mul_f32 v[188:189], v[158:159], v[110:111]
	v_pk_mul_f32 v[202:203], v[180:181], v[108:109]
	v_cvt_pk_bf16_f32 v198, v188, v189
	v_cvt_pk_bf16_f32 v199, v136, v137
	v_cvt_pk_bf16_f32 v200, v200, v201
	s_nop 0
	v_cvt_pk_bf16_f32 v201, v202, v203
	global_store_dwordx4 v[120:121], v[198:201], off
	v_mov_b32_e32 v121, v106
	v_mov_b32_e32 v106, v111
	v_mov_b32_e32 v111, v108
	v_mov_b32_e32 v108, v113
	v_mov_b32_e32 v120, v110
	v_pk_mul_f32 v[106:107], v[106:107], v[106:107]
	v_mov_b32_e32 v110, v112
	v_pk_mul_f32 v[108:109], v[108:109], v[108:109]
	v_pk_fma_f32 v[106:107], v[120:121], v[120:121], v[106:107]
	v_pk_fma_f32 v[108:109], v[110:111], v[110:111], v[108:109]
	s_nop 0
	v_pk_add_f32 v[106:107], v[106:107], v[108:109]
	s_nop 0
	v_add_f32_e32 v129, v106, v107
.LBB0_723:
	s_mov_b64 s[4:5], 0x48000
	v_lshl_add_u64 v[106:107], v[182:183], 0, s[4:5]
	v_lshl_add_u64 v[112:113], v[106:107], 0, v[156:157]
	v_lshlrev_b64 v[110:111], 2, v[112:113]
	v_lshl_add_u64 v[108:109], s[44:45], 0, v[110:111]
	v_lshl_add_u64 v[120:121], v[112:113], 1, s[90:91]
	v_lshl_add_u64 v[110:111], s[70:71], 0, v[110:111]
	s_and_b64 vcc, exec, s[2:3]
	s_waitcnt vmcnt(7)
	v_mov_b32_e32 v198, v232
	v_mov_b32_e32 v199, v233
	v_mov_b32_e32 v200, v234
	v_mov_b32_e32 v201, v235
	v_mov_b32_e32 v202, v236
	v_mov_b32_e32 v203, v237
	v_mov_b32_e32 v204, v238
	v_mov_b32_e32 v205, v239
	v_mov_b32_e32 v206, v244
	v_mov_b32_e32 v207, v245
	v_mov_b32_e32 v208, v246
	v_mov_b32_e32 v209, v247
	s_mov_b32 s98, 0x160000
	s_mov_b32 s99, 0
	v_lshl_add_u64 v[252:253], v[248:249], 0, s[98:99]
	s_mov_b32 s98, 0xb0000
	v_lshl_add_u64 v[254:255], v[250:251], 0, s[98:99]
	global_load_dwordx4 v[232:235], v[252:253], off offset:16 nt
	global_load_dwordx4 v[236:239], v[252:253], off nt
	global_load_dwordx4 v[244:247], v[254:255], off nt
	v_lshlrev_b32_e32 v120, 16, v206
	v_and_b32_e32 v121, 0xffff0000, v206
	v_lshlrev_b32_e32 v136, 16, v207
	v_and_b32_e32 v137, 0xffff0000, v207
	v_pk_add_f32 v[120:121], v[202:203], v[120:121]
	v_lshlrev_b32_e32 v188, 16, v208
	v_and_b32_e32 v189, 0xffff0000, v208
	v_lshlrev_b32_e32 v202, 16, v209
	v_and_b32_e32 v203, 0xffff0000, v209
	v_pk_add_f32 v[136:137], v[204:205], v[136:137]
	v_pk_add_f32 v[200:201], v[200:201], v[202:203]
	v_pk_add_f32 v[188:189], v[198:199], v[188:189]
	v_pk_fma_f32 v[96:97], v[96:97], v[104:105], v[136:137]
	v_pk_fma_f32 v[94:95], v[94:95], v[102:103], v[120:121]
	v_pk_fma_f32 v[92:93], v[92:93], v[100:101], v[200:201]
	v_pk_fma_f32 v[90:91], v[90:91], v[98:99], v[188:189]
	global_store_dwordx4 v[110:111], v[94:97], off
	global_store_dwordx4 v[110:111], v[90:93], off offset:16
	s_cbranch_vccnz .LBB0_725
	v_pk_mul_f32 v[200:201], v[178:179], v[90:91]
	v_lshl_add_u64 v[112:113], v[112:113], 1, s[96:97]
	v_pk_mul_f32 v[120:121], v[160:161], v[96:97]
	v_pk_mul_f32 v[136:137], v[158:159], v[94:95]
	v_pk_mul_f32 v[188:189], v[180:181], v[92:93]
	v_cvt_pk_bf16_f32 v198, v136, v137
	v_cvt_pk_bf16_f32 v199, v120, v121
	v_cvt_pk_bf16_f32 v200, v200, v201
	s_nop 0
	v_cvt_pk_bf16_f32 v201, v188, v189
	global_store_dwordx4 v[112:113], v[198:201], off
	v_mov_b32_e32 v113, v90
	v_mov_b32_e32 v90, v95
	v_mov_b32_e32 v95, v92
	v_mov_b32_e32 v92, v97
	v_mov_b32_e32 v112, v94
	v_pk_mul_f32 v[90:91], v[90:91], v[90:91]
	v_mov_b32_e32 v94, v96
	v_pk_mul_f32 v[92:93], v[92:93], v[92:93]
	v_pk_fma_f32 v[90:91], v[112:113], v[112:113], v[90:91]
	v_pk_fma_f32 v[92:93], v[94:95], v[94:95], v[92:93]
	s_nop 0
	v_pk_add_f32 v[90:91], v[90:91], v[92:93]
	s_nop 0
	v_add_f32_e32 v128, v90, v91
; __device__ __forceinline__ unsigned cvt_pk_bf16(float lo, float hi) { unsigned r; asm volatile("v_cvt_pk_bf16_f32 %0, %1, %2" : "=v"(r) : "v"(lo), "v"(hi)); return r; }
;     __device__ __forceinline__ void operator()(const f32x4 (&acc)[2][2][4][2], const Unit& u, int wr, int wc, int fr, int fq) const {
;     ...
;                 for (int m = 0; m < 4; ++m) { const size_t off = (size_t)(row0 + ai * HALF + m * 16) * 2048 + col0 + bj * HALF;
;                     f32x4 x0 = __builtin_nontemporal_load((const f32x4*)(base + off)), x1 = __builtin_nontemporal_load((const f32x4*)(base + off + 4));
;                     if constexpr (HAS_DIN) { const u32x4 dw = __builtin_nontemporal_load((const u32x4*)(dbuf + off));
;                         x0 += (f32x4){__builtin_bit_cast(float, dw.x << 16), __builtin_bit_cast(float, dw.x & 0xffff0000u), __builtin_bit_cast(float, dw.y << 16), __builtin_bit_cast(float, dw.y & 0xffff0000u)};
;                         x1 += (f32x4){__builtin_bit_cast(float, dw.z << 16), __builtin_bit_cast(float, dw.z & 0xffff0000u), __builtin_bit_cast(float, dw.w << 16), __builtin_bit_cast(float, dw.w & 0xffff0000u)}; }
;                     f32x4 o0, o1;
;                     if constexpr (OUT_DELTA) { const f32x4 d0 = g0 * acc[ai][bj][m][0], d1 = g1 * acc[ai][bj][m][1];
;                         u32x4 w; w.x = cvt_pk_bf16(d0[0], d0[1]); w.y = cvt_pk_bf16(d0[2], d0[3]); w.z = cvt_pk_bf16(d1[0], d1[1]); w.w = cvt_pk_bf16(d1[2], d1[3]);
;                         *(u32x4*)(dbuf + off) = w;
;                         o0 = x0 + (f32x4){__builtin_bit_cast(float, w.x << 16), __builtin_bit_cast(float, w.x & 0xffff0000u), __builtin_bit_cast(float, w.y << 16), __builtin_bit_cast(float, w.y & 0xffff0000u)};
;                         o1 = x1 + (f32x4){__builtin_bit_cast(float, w.z << 16), __builtin_bit_cast(float, w.z & 0xffff0000u), __builtin_bit_cast(float, w.w << 16), __builtin_bit_cast(float, w.w & 0xffff0000u)}; }
;                     else { o0 = x0 + g0 * acc[ai][bj][m][0]; o1 = x1 + g1 * acc[ai][bj][m][1]; *(f32x4*)(out + off) = o0; *(f32x4*)(out + off + 4) = o1; }
;                     if (Hn) { const f32x4 h0 = o0 * G0, h1 = o1 * G1;
;                         u32x4 w; w.x = cvt_pk_bf16(h0[0], h0[1]); w.y = cvt_pk_bf16(h0[2], h0[3]); w.z = cvt_pk_bf16(h1[0], h1[1]); w.w = cvt_pk_bf16(h1[2], h1[3]);
;                         *(u32x4*)(Hn + off) = w;
.LBB0_725:
	s_mov_b64 s[4:5], 0x50000
	v_lshl_add_u64 v[90:91], v[182:183], 0, s[4:5]
	v_lshl_add_u64 v[96:97], v[90:91], 0, v[156:157]
	v_lshlrev_b64 v[94:95], 2, v[96:97]
	v_lshl_add_u64 v[92:93], s[44:45], 0, v[94:95]
	v_lshl_add_u64 v[112:113], v[96:97], 1, s[90:91]
	v_lshl_add_u64 v[94:95], s[70:71], 0, v[94:95]
	s_and_b64 vcc, exec, s[2:3]
	s_waitcnt vmcnt(7)
	v_mov_b32_e32 v198, v220
	v_mov_b32_e32 v199, v221
	v_mov_b32_e32 v200, v222
	v_mov_b32_e32 v201, v223
	v_mov_b32_e32 v202, v224
	v_mov_b32_e32 v203, v225
	v_mov_b32_e32 v204, v226
	v_mov_b32_e32 v205, v227
	v_mov_b32_e32 v206, v228
	v_mov_b32_e32 v207, v229
	v_mov_b32_e32 v208, v230
	v_mov_b32_e32 v209, v231
	global_load_dwordx4 v[220:223], v[248:249], off offset:528 nt
	global_load_dwordx4 v[224:227], v[248:249], off offset:512 nt
	global_load_dwordx4 v[228:231], v[250:251], off offset:256 nt
	v_lshlrev_b32_e32 v112, 16, v206
	v_and_b32_e32 v113, 0xffff0000, v206
	v_lshlrev_b32_e32 v120, 16, v207
	v_and_b32_e32 v121, 0xffff0000, v207
	v_lshlrev_b32_e32 v136, 16, v208
	v_and_b32_e32 v137, 0xffff0000, v208
	v_lshlrev_b32_e32 v188, 16, v209
	v_and_b32_e32 v189, 0xffff0000, v209
	v_pk_add_f32 v[120:121], v[204:205], v[120:121]
	v_pk_add_f32 v[112:113], v[202:203], v[112:113]
	v_pk_add_f32 v[188:189], v[200:201], v[188:189]
	v_pk_add_f32 v[136:137], v[198:199], v[136:137]
	v_pk_fma_f32 v[88:89], v[88:89], v[104:105], v[120:121]
	v_pk_fma_f32 v[86:87], v[86:87], v[102:103], v[112:113]
	v_pk_fma_f32 v[84:85], v[84:85], v[100:101], v[188:189]
	v_pk_fma_f32 v[82:83], v[82:83], v[98:99], v[136:137]
	v_mov_b32_e32 v112, 0
	v_mov_b32_e32 v113, 0
	global_store_dwordx4 v[94:95], v[86:89], off
	global_store_dwordx4 v[94:95], v[82:85], off offset:16
	s_cbranch_vccnz .LBB0_727
	v_pk_mul_f32 v[200:201], v[178:179], v[82:83]
	v_lshl_add_u64 v[96:97], v[96:97], 1, s[96:97]
	v_pk_mul_f32 v[120:121], v[160:161], v[88:89]
	v_pk_mul_f32 v[136:137], v[158:159], v[86:87]
	v_pk_mul_f32 v[188:189], v[180:181], v[84:85]
	v_cvt_pk_bf16_f32 v198, v136, v137
	v_cvt_pk_bf16_f32 v199, v120, v121
	v_cvt_pk_bf16_f32 v200, v200, v201
	s_nop 0
	v_cvt_pk_bf16_f32 v201, v188, v189
	global_store_dwordx4 v[96:97], v[198:201], off
	v_mov_b32_e32 v97, v82
	v_mov_b32_e32 v82, v87
	v_mov_b32_e32 v87, v84
	v_mov_b32_e32 v84, v89
	v_mov_b32_e32 v96, v86
	v_pk_mul_f32 v[82:83], v[82:83], v[82:83]
	v_mov_b32_e32 v86, v88
	v_pk_mul_f32 v[84:85], v[84:85], v[84:85]
	v_pk_fma_f32 v[82:83], v[96:97], v[96:97], v[82:83]
	v_pk_fma_f32 v[84:85], v[86:87], v[86:87], v[84:85]
	s_nop 0
	v_pk_add_f32 v[82:83], v[82:83], v[84:85]
	s_nop 0
	v_add_f32_e32 v113, v82, v83
.LBB0_727:
	s_mov_b64 s[4:5], 0x58000
	v_lshl_add_u64 v[82:83], v[182:183], 0, s[4:5]
	v_lshl_add_u64 v[88:89], v[82:83], 0, v[156:157]
	v_lshlrev_b64 v[86:87], 2, v[88:89]
	v_lshl_add_u64 v[84:85], s[44:45], 0, v[86:87]
	v_lshl_add_u64 v[96:97], v[88:89], 1, s[90:91]
	v_lshl_add_u64 v[86:87], s[70:71], 0, v[86:87]
	s_and_b64 vcc, exec, s[2:3]
	s_waitcnt vmcnt(7)
	v_mov_b32_e32 v198, v232
	v_mov_b32_e32 v199, v233
	v_mov_b32_e32 v200, v234
	v_mov_b32_e32 v201, v235
	v_mov_b32_e32 v202, v236
	v_mov_b32_e32 v203, v237
	v_mov_b32_e32 v204, v238
	v_mov_b32_e32 v205, v239
	v_mov_b32_e32 v206, v244
	v_mov_b32_e32 v207, v245
	v_mov_b32_e32 v208, v246
	v_mov_b32_e32 v209, v247
	s_mov_b32 s98, 0x20000
	s_mov_b32 s99, 0
	v_lshl_add_u64 v[252:253], v[248:249], 0, s[98:99]
	s_mov_b32 s98, 0x10000
	v_lshl_add_u64 v[254:255], v[250:251], 0, s[98:99]
	global_load_dwordx4 v[232:235], v[252:253], off offset:528 nt
	global_load_dwordx4 v[236:239], v[252:253], off offset:512 nt
	global_load_dwordx4 v[244:247], v[254:255], off offset:256 nt
	v_lshlrev_b32_e32 v96, 16, v206
	v_and_b32_e32 v97, 0xffff0000, v206
	v_lshlrev_b32_e32 v120, 16, v207
	v_and_b32_e32 v121, 0xffff0000, v207
	v_lshlrev_b32_e32 v136, 16, v208
	v_and_b32_e32 v137, 0xffff0000, v208
	v_lshlrev_b32_e32 v188, 16, v209
	v_and_b32_e32 v189, 0xffff0000, v209
	v_pk_add_f32 v[120:121], v[204:205], v[120:121]
	v_pk_add_f32 v[96:97], v[202:203], v[96:97]
	v_pk_add_f32 v[188:189], v[200:201], v[188:189]
	v_pk_add_f32 v[136:137], v[198:199], v[136:137]
	v_pk_fma_f32 v[80:81], v[80:81], v[104:105], v[120:121]
	v_pk_fma_f32 v[78:79], v[78:79], v[102:103], v[96:97]
	v_pk_fma_f32 v[76:77], v[76:77], v[100:101], v[188:189]
	v_pk_fma_f32 v[74:75], v[74:75], v[98:99], v[136:137]
	global_store_dwordx4 v[86:87], v[78:81], off
	global_store_dwordx4 v[86:87], v[74:77], off offset:16
	s_cbranch_vccnz .LBB0_729
	v_pk_mul_f32 v[98:99], v[160:161], v[80:81]
	v_pk_mul_f32 v[96:97], v[158:159], v[78:79]
	v_lshl_add_u64 v[88:89], v[88:89], 1, s[96:97]
	v_pk_mul_f32 v[100:101], v[180:181], v[76:77]
	v_pk_mul_f32 v[102:103], v[178:179], v[74:75]
	v_cvt_pk_bf16_f32 v96, v96, v97
	v_cvt_pk_bf16_f32 v97, v98, v99
	s_nop 0
	v_cvt_pk_bf16_f32 v98, v102, v103
	v_cvt_pk_bf16_f32 v99, v100, v101
	global_store_dwordx4 v[88:89], v[96:99], off
	v_mov_b32_e32 v89, v74
	v_mov_b32_e32 v74, v79
	v_mov_b32_e32 v79, v76
	v_mov_b32_e32 v76, v81
	v_mov_b32_e32 v88, v78
	v_pk_mul_f32 v[74:75], v[74:75], v[74:75]
	v_mov_b32_e32 v78, v80
	v_pk_mul_f32 v[76:77], v[76:77], v[76:77]
	v_pk_fma_f32 v[74:75], v[88:89], v[88:89], v[74:75]
	v_pk_fma_f32 v[76:77], v[78:79], v[78:79], v[76:77]
	s_nop 0
	v_pk_add_f32 v[74:75], v[74:75], v[76:77]
	s_nop 0
	v_add_f32_e32 v112, v74, v75
; __device__ __forceinline__ unsigned cvt_pk_bf16(float lo, float hi) { unsigned r; asm volatile("v_cvt_pk_bf16_f32 %0, %1, %2" : "=v"(r) : "v"(lo), "v"(hi)); return r; }
;     __device__ __forceinline__ void operator()(const f32x4 (&acc)[2][2][4][2], const Unit& u, int wr, int wc, int fr, int fq) const {
;     ...
;                 for (int m = 0; m < 4; ++m) { const size_t off = (size_t)(row0 + ai * HALF + m * 16) * 2048 + col0 + bj * HALF;
;                     f32x4 x0 = __builtin_nontemporal_load((const f32x4*)(base + off)), x1 = __builtin_nontemporal_load((const f32x4*)(base + off + 4));
;                     if constexpr (HAS_DIN) { const u32x4 dw = __builtin_nontemporal_load((const u32x4*)(dbuf + off));
;                         x0 += (f32x4){__builtin_bit_cast(float, dw.x << 16), __builtin_bit_cast(float, dw.x & 0xffff0000u), __builtin_bit_cast(float, dw.y << 16), __builtin_bit_cast(float, dw.y & 0xffff0000u)};
;                         x1 += (f32x4){__builtin_bit_cast(float, dw.z << 16), __builtin_bit_cast(float, dw.z & 0xffff0000u), __builtin_bit_cast(float, dw.w << 16), __builtin_bit_cast(float, dw.w & 0xffff0000u)}; }
;                     f32x4 o0, o1;
;                     if constexpr (OUT_DELTA) { const f32x4 d0 = g0 * acc[ai][bj][m][0], d1 = g1 * acc[ai][bj][m][1];
;                         u32x4 w; w.x = cvt_pk_bf16(d0[0], d0[1]); w.y = cvt_pk_bf16(d0[2], d0[3]); w.z = cvt_pk_bf16(d1[0], d1[1]); w.w = cvt_pk_bf16(d1[2], d1[3]);
;                         *(u32x4*)(dbuf + off) = w;
;                         o0 = x0 + (f32x4){__builtin_bit_cast(float, w.x << 16), __builtin_bit_cast(float, w.x & 0xffff0000u), __builtin_bit_cast(float, w.y << 16), __builtin_bit_cast(float, w.y & 0xffff0000u)};
;                         o1 = x1 + (f32x4){__builtin_bit_cast(float, w.z << 16), __builtin_bit_cast(float, w.z & 0xffff0000u), __builtin_bit_cast(float, w.w << 16), __builtin_bit_cast(float, w.w & 0xffff0000u)}; }
;                     else { o0 = x0 + g0 * acc[ai][bj][m][0]; o1 = x1 + g1 * acc[ai][bj][m][1]; *(f32x4*)(out + off) = o0; *(f32x4*)(out + off + 4) = o1; }
;                     if (Hn) { const f32x4 h0 = o0 * G0, h1 = o1 * G1;
;                         u32x4 w; w.x = cvt_pk_bf16(h0[0], h0[1]); w.y = cvt_pk_bf16(h0[2], h0[3]); w.z = cvt_pk_bf16(h1[0], h1[1]); w.w = cvt_pk_bf16(h1[2], h1[3]);
;                         *(u32x4*)(Hn + off) = w;
.LBB0_729:
	v_or_b32_e32 v156, 0x80, v156
	v_lshl_add_u64 v[74:75], v[182:183], 0, v[156:157]
	v_lshl_add_u64 v[80:81], v[74:75], 1, s[90:91]
	s_and_b64 vcc, exec, s[2:3]
	s_waitcnt vmcnt(7)
	v_mov_b32_e32 v76, v220
	v_mov_b32_e32 v77, v221
	v_mov_b32_e32 v78, v222
	v_mov_b32_e32 v79, v223
	v_mov_b32_e32 v96, v224
	v_mov_b32_e32 v97, v225
	v_mov_b32_e32 v98, v226
	v_mov_b32_e32 v99, v227
	v_mov_b32_e32 v100, v228
	v_mov_b32_e32 v101, v229
	v_mov_b32_e32 v102, v230
	v_mov_b32_e32 v103, v231
	s_mov_b32 s98, 0x40000
	s_mov_b32 s99, 0
	v_lshl_add_u64 v[252:253], v[248:249], 0, s[98:99]
	s_mov_b32 s98, 0x20000
	v_lshl_add_u64 v[254:255], v[250:251], 0, s[98:99]
	global_load_dwordx4 v[220:223], v[252:253], off offset:528 nt
	global_load_dwordx4 v[224:227], v[252:253], off offset:512 nt
	global_load_dwordx4 v[228:231], v[254:255], off offset:256 nt
	v_lshlrev_b32_e32 v80, 16, v100
	v_and_b32_e32 v81, 0xffff0000, v100
	v_lshlrev_b32_e32 v88, 16, v101
	v_and_b32_e32 v89, 0xffff0000, v101
	v_pk_add_f32 v[80:81], v[96:97], v[80:81]
	v_pk_add_f32 v[88:89], v[98:99], v[88:89]
	v_lshlrev_b32_e32 v96, 16, v102
	v_and_b32_e32 v97, 0xffff0000, v102
	v_lshlrev_b32_e32 v98, 16, v103
	v_and_b32_e32 v99, 0xffff0000, v103
	v_pk_add_f32 v[76:77], v[76:77], v[96:97]
	v_pk_add_f32 v[78:79], v[78:79], v[98:99]
	v_pk_fma_f32 v[72:73], v[72:73], v[40:41], v[88:89]
	v_pk_fma_f32 v[70:71], v[70:71], v[38:39], v[80:81]
	v_pk_fma_f32 v[68:69], v[68:69], v[36:37], v[78:79]
	v_pk_fma_f32 v[66:67], v[66:67], v[34:35], v[76:77]
	global_store_dwordx4 v[186:187], v[70:73], off offset:512
	global_store_dwordx4 v[186:187], v[66:69], off offset:528
	s_cbranch_vccnz .LBB0_731
	v_pk_mul_f32 v[78:79], v[150:151], v[72:73]
	v_pk_mul_f32 v[76:77], v[148:149], v[70:71]
	v_lshl_add_u64 v[74:75], v[74:75], 1, s[96:97]
	v_pk_mul_f32 v[80:81], v[154:155], v[68:69]
	v_pk_mul_f32 v[88:89], v[152:153], v[66:67]
	v_cvt_pk_bf16_f32 v76, v76, v77
	v_cvt_pk_bf16_f32 v77, v78, v79
	s_nop 0
	v_cvt_pk_bf16_f32 v78, v88, v89
	v_cvt_pk_bf16_f32 v79, v80, v81
	global_store_dwordx4 v[74:75], v[76:79], off
	v_mov_b32_e32 v75, v66
	v_mov_b32_e32 v66, v71
	v_mov_b32_e32 v71, v68
	v_mov_b32_e32 v68, v73
	v_mov_b32_e32 v74, v70
	v_pk_mul_f32 v[66:67], v[66:67], v[66:67]
	v_mov_b32_e32 v70, v72
	v_pk_mul_f32 v[68:69], v[68:69], v[68:69]
	v_pk_fma_f32 v[66:67], v[74:75], v[74:75], v[66:67]
	v_pk_fma_f32 v[68:69], v[70:71], v[70:71], v[68:69]
	s_nop 0
	v_pk_add_f32 v[66:67], v[66:67], v[68:69]
	s_nop 0
	v_add_f32_e32 v66, v66, v67
	v_add_f32_e32 v196, v196, v66
.LBB0_731:
	s_nop 0
	v_lshl_add_u64 v[66:67], v[138:139], 0, v[156:157]
	v_lshl_add_u64 v[76:77], v[66:67], 1, s[90:91]
	s_and_b64 vcc, exec, s[2:3]
	s_waitcnt vmcnt(7)
	v_mov_b32_e32 v68, v232
	v_mov_b32_e32 v69, v233
	v_mov_b32_e32 v70, v234
	v_mov_b32_e32 v71, v235
	v_mov_b32_e32 v72, v236
	v_mov_b32_e32 v73, v237
	v_mov_b32_e32 v74, v238
	v_mov_b32_e32 v75, v239
	v_mov_b32_e32 v76, v244
	v_mov_b32_e32 v77, v245
	v_mov_b32_e32 v78, v246
	v_mov_b32_e32 v79, v247
	s_mov_b32 s98, 0x60000
	s_mov_b32 s99, 0
	v_lshl_add_u64 v[252:253], v[248:249], 0, s[98:99]
	s_mov_b32 s98, 0x30000
	v_lshl_add_u64 v[254:255], v[250:251], 0, s[98:99]
	global_load_dwordx4 v[232:235], v[252:253], off offset:528 nt
	global_load_dwordx4 v[236:239], v[252:253], off offset:512 nt
	global_load_dwordx4 v[244:247], v[254:255], off offset:256 nt
	v_lshlrev_b32_e32 v80, 16, v76
	v_and_b32_e32 v81, 0xffff0000, v76
	v_lshlrev_b32_e32 v76, 16, v77
	v_and_b32_e32 v77, 0xffff0000, v77
	v_pk_add_f32 v[74:75], v[74:75], v[76:77]
	v_lshlrev_b32_e32 v76, 16, v78
	v_and_b32_e32 v77, 0xffff0000, v78
	v_lshlrev_b32_e32 v78, 16, v79
	v_and_b32_e32 v79, 0xffff0000, v79
	v_pk_add_f32 v[72:73], v[72:73], v[80:81]
	v_pk_add_f32 v[68:69], v[68:69], v[76:77]
	v_pk_add_f32 v[70:71], v[70:71], v[78:79]
	v_pk_fma_f32 v[64:65], v[64:65], v[40:41], v[74:75]
	v_pk_fma_f32 v[62:63], v[62:63], v[38:39], v[72:73]
	v_pk_fma_f32 v[60:61], v[60:61], v[36:37], v[70:71]
	v_pk_fma_f32 v[58:59], v[58:59], v[34:35], v[68:69]
	global_store_dwordx4 v[142:143], v[62:65], off offset:512
	global_store_dwordx4 v[142:143], v[58:61], off offset:528
	s_cbranch_vccnz .LBB0_733
	v_pk_mul_f32 v[70:71], v[150:151], v[64:65]
	v_pk_mul_f32 v[68:69], v[148:149], v[62:63]
	v_lshl_add_u64 v[66:67], v[66:67], 1, s[96:97]
	v_pk_mul_f32 v[72:73], v[154:155], v[60:61]
	v_pk_mul_f32 v[74:75], v[152:153], v[58:59]
	v_cvt_pk_bf16_f32 v68, v68, v69
	v_cvt_pk_bf16_f32 v69, v70, v71
	s_nop 0
	v_cvt_pk_bf16_f32 v70, v74, v75
	v_cvt_pk_bf16_f32 v71, v72, v73
	global_store_dwordx4 v[66:67], v[68:71], off
	v_mov_b32_e32 v67, v58
	v_mov_b32_e32 v58, v63
	v_mov_b32_e32 v63, v60
	v_mov_b32_e32 v60, v65
	v_mov_b32_e32 v66, v62
	v_pk_mul_f32 v[58:59], v[58:59], v[58:59]
	v_mov_b32_e32 v62, v64
	v_pk_mul_f32 v[60:61], v[60:61], v[60:61]
	v_pk_fma_f32 v[58:59], v[66:67], v[66:67], v[58:59]
	v_pk_fma_f32 v[60:61], v[62:63], v[62:63], v[60:61]
	s_nop 0
	v_pk_add_f32 v[58:59], v[58:59], v[60:61]
	s_nop 0
	v_add_f32_e32 v58, v58, v59
	v_add_f32_e32 v195, v195, v58
; __device__ __forceinline__ unsigned cvt_pk_bf16(float lo, float hi) { unsigned r; asm volatile("v_cvt_pk_bf16_f32 %0, %1, %2" : "=v"(r) : "v"(lo), "v"(hi)); return r; }
;     __device__ __forceinline__ void operator()(const f32x4 (&acc)[2][2][4][2], const Unit& u, int wr, int wc, int fr, int fq) const {
;     ...
;                 for (int m = 0; m < 4; ++m) { const size_t off = (size_t)(row0 + ai * HALF + m * 16) * 2048 + col0 + bj * HALF;
;                     f32x4 x0 = __builtin_nontemporal_load((const f32x4*)(base + off)), x1 = __builtin_nontemporal_load((const f32x4*)(base + off + 4));
;                     if constexpr (HAS_DIN) { const u32x4 dw = __builtin_nontemporal_load((const u32x4*)(dbuf + off));
;                         x0 += (f32x4){__builtin_bit_cast(float, dw.x << 16), __builtin_bit_cast(float, dw.x & 0xffff0000u), __builtin_bit_cast(float, dw.y << 16), __builtin_bit_cast(float, dw.y & 0xffff0000u)};
;                         x1 += (f32x4){__builtin_bit_cast(float, dw.z << 16), __builtin_bit_cast(float, dw.z & 0xffff0000u), __builtin_bit_cast(float, dw.w << 16), __builtin_bit_cast(float, dw.w & 0xffff0000u)}; }
;                     f32x4 o0, o1;
;                     if constexpr (OUT_DELTA) { const f32x4 d0 = g0 * acc[ai][bj][m][0], d1 = g1 * acc[ai][bj][m][1];
;                         u32x4 w; w.x = cvt_pk_bf16(d0[0], d0[1]); w.y = cvt_pk_bf16(d0[2], d0[3]); w.z = cvt_pk_bf16(d1[0], d1[1]); w.w = cvt_pk_bf16(d1[2], d1[3]);
;                         *(u32x4*)(dbuf + off) = w;
;                         o0 = x0 + (f32x4){__builtin_bit_cast(float, w.x << 16), __builtin_bit_cast(float, w.x & 0xffff0000u), __builtin_bit_cast(float, w.y << 16), __builtin_bit_cast(float, w.y & 0xffff0000u)};
;                         o1 = x1 + (f32x4){__builtin_bit_cast(float, w.z << 16), __builtin_bit_cast(float, w.z & 0xffff0000u), __builtin_bit_cast(float, w.w << 16), __builtin_bit_cast(float, w.w & 0xffff0000u)}; }
;                     else { o0 = x0 + g0 * acc[ai][bj][m][0]; o1 = x1 + g1 * acc[ai][bj][m][1]; *(f32x4*)(out + off) = o0; *(f32x4*)(out + off + 4) = o1; }
;                     if (Hn) { const f32x4 h0 = o0 * G0, h1 = o1 * G1;
;                         u32x4 w; w.x = cvt_pk_bf16(h0[0], h0[1]); w.y = cvt_pk_bf16(h0[2], h0[3]); w.z = cvt_pk_bf16(h1[0], h1[1]); w.w = cvt_pk_bf16(h1[2], h1[3]);
;                         *(u32x4*)(Hn + off) = w;
.LBB0_733:
	s_nop 0
	v_lshl_add_u64 v[58:59], v[130:131], 0, v[156:157]
	v_lshl_add_u64 v[68:69], v[58:59], 1, s[90:91]
	s_and_b64 vcc, exec, s[2:3]
	s_waitcnt vmcnt(7)
	v_mov_b32_e32 v60, v220
	v_mov_b32_e32 v61, v221
	v_mov_b32_e32 v62, v222
	v_mov_b32_e32 v63, v223
	v_mov_b32_e32 v64, v224
	v_mov_b32_e32 v65, v225
	v_mov_b32_e32 v66, v226
	v_mov_b32_e32 v67, v227
	v_mov_b32_e32 v68, v228
	v_mov_b32_e32 v69, v229
	v_mov_b32_e32 v70, v230
	v_mov_b32_e32 v71, v231
	s_mov_b32 s98, 0x100000
	s_mov_b32 s99, 0
	v_lshl_add_u64 v[252:253], v[248:249], 0, s[98:99]
	s_mov_b32 s98, 0x80000
	v_lshl_add_u64 v[254:255], v[250:251], 0, s[98:99]
	global_load_dwordx4 v[220:223], v[252:253], off offset:528 nt
	global_load_dwordx4 v[224:227], v[252:253], off offset:512 nt
	global_load_dwordx4 v[228:231], v[254:255], off offset:256 nt
	v_lshlrev_b32_e32 v72, 16, v68
	v_and_b32_e32 v73, 0xffff0000, v68
	v_lshlrev_b32_e32 v68, 16, v69
	v_and_b32_e32 v69, 0xffff0000, v69
	v_pk_add_f32 v[66:67], v[66:67], v[68:69]
	v_lshlrev_b32_e32 v68, 16, v70
	v_and_b32_e32 v69, 0xffff0000, v70
	v_lshlrev_b32_e32 v70, 16, v71
	v_and_b32_e32 v71, 0xffff0000, v71
	v_pk_add_f32 v[64:65], v[64:65], v[72:73]
	v_pk_add_f32 v[60:61], v[60:61], v[68:69]
	v_pk_add_f32 v[62:63], v[62:63], v[70:71]
	v_pk_fma_f32 v[56:57], v[56:57], v[40:41], v[66:67]
	v_pk_fma_f32 v[54:55], v[54:55], v[38:39], v[64:65]
	v_pk_fma_f32 v[52:53], v[52:53], v[36:37], v[62:63]
	v_pk_fma_f32 v[50:51], v[50:51], v[34:35], v[60:61]
	global_store_dwordx4 v[134:135], v[54:57], off offset:512
	global_store_dwordx4 v[134:135], v[50:53], off offset:528
	s_cbranch_vccnz .LBB0_735
	v_pk_mul_f32 v[62:63], v[150:151], v[56:57]
	v_pk_mul_f32 v[60:61], v[148:149], v[54:55]
	v_lshl_add_u64 v[58:59], v[58:59], 1, s[96:97]
	v_pk_mul_f32 v[64:65], v[154:155], v[52:53]
	v_pk_mul_f32 v[66:67], v[152:153], v[50:51]
	v_cvt_pk_bf16_f32 v60, v60, v61
	v_cvt_pk_bf16_f32 v61, v62, v63
	s_nop 0
	v_cvt_pk_bf16_f32 v62, v66, v67
	v_cvt_pk_bf16_f32 v63, v64, v65
	global_store_dwordx4 v[58:59], v[60:63], off
	v_mov_b32_e32 v59, v50
	v_mov_b32_e32 v50, v55
	v_mov_b32_e32 v55, v52
	v_mov_b32_e32 v52, v57
	v_mov_b32_e32 v58, v54
	v_pk_mul_f32 v[50:51], v[50:51], v[50:51]
	v_mov_b32_e32 v54, v56
	v_pk_mul_f32 v[52:53], v[52:53], v[52:53]
	v_pk_fma_f32 v[50:51], v[58:59], v[58:59], v[50:51]
	v_pk_fma_f32 v[52:53], v[54:55], v[54:55], v[52:53]
	s_nop 0
	v_pk_add_f32 v[50:51], v[50:51], v[52:53]
	s_nop 0
	v_add_f32_e32 v50, v50, v51
	v_add_f32_e32 v145, v145, v50
.LBB0_735:
	s_nop 0
	v_lshl_add_u64 v[50:51], v[122:123], 0, v[156:157]
	v_lshl_add_u64 v[60:61], v[50:51], 1, s[90:91]
	s_and_b64 vcc, exec, s[2:3]
	s_waitcnt vmcnt(7)
	v_mov_b32_e32 v52, v232
	v_mov_b32_e32 v53, v233
	v_mov_b32_e32 v54, v234
	v_mov_b32_e32 v55, v235
	v_mov_b32_e32 v56, v236
	v_mov_b32_e32 v57, v237
	v_mov_b32_e32 v58, v238
	v_mov_b32_e32 v59, v239
	v_mov_b32_e32 v60, v244
	v_mov_b32_e32 v61, v245
	v_mov_b32_e32 v62, v246
	v_mov_b32_e32 v63, v247
	s_mov_b32 s98, 0x120000
	s_mov_b32 s99, 0
	v_lshl_add_u64 v[252:253], v[248:249], 0, s[98:99]
	s_mov_b32 s98, 0x90000
	v_lshl_add_u64 v[254:255], v[250:251], 0, s[98:99]
	global_load_dwordx4 v[232:235], v[252:253], off offset:528 nt
	global_load_dwordx4 v[236:239], v[252:253], off offset:512 nt
	global_load_dwordx4 v[244:247], v[254:255], off offset:256 nt
	v_lshlrev_b32_e32 v64, 16, v60
	v_and_b32_e32 v65, 0xffff0000, v60
	v_lshlrev_b32_e32 v60, 16, v61
	v_and_b32_e32 v61, 0xffff0000, v61
	v_pk_add_f32 v[58:59], v[58:59], v[60:61]
	v_lshlrev_b32_e32 v60, 16, v62
	v_and_b32_e32 v61, 0xffff0000, v62
	v_lshlrev_b32_e32 v62, 16, v63
	v_and_b32_e32 v63, 0xffff0000, v63
	v_pk_add_f32 v[56:57], v[56:57], v[64:65]
	v_pk_add_f32 v[52:53], v[52:53], v[60:61]
	v_pk_add_f32 v[54:55], v[54:55], v[62:63]
	v_pk_fma_f32 v[48:49], v[48:49], v[40:41], v[58:59]
	v_pk_fma_f32 v[46:47], v[46:47], v[38:39], v[56:57]
	v_pk_fma_f32 v[44:45], v[44:45], v[36:37], v[54:55]
	v_pk_fma_f32 v[42:43], v[42:43], v[34:35], v[52:53]
	global_store_dwordx4 v[126:127], v[46:49], off offset:512
	global_store_dwordx4 v[126:127], v[42:45], off offset:528
	s_cbranch_vccnz .LBB0_737
	v_pk_mul_f32 v[54:55], v[150:151], v[48:49]
	v_pk_mul_f32 v[52:53], v[148:149], v[46:47]
	v_lshl_add_u64 v[50:51], v[50:51], 1, s[96:97]
	v_pk_mul_f32 v[56:57], v[154:155], v[44:45]
	v_pk_mul_f32 v[58:59], v[152:153], v[42:43]
	v_cvt_pk_bf16_f32 v52, v52, v53
	v_cvt_pk_bf16_f32 v53, v54, v55
	s_nop 0
	v_cvt_pk_bf16_f32 v54, v58, v59
	v_cvt_pk_bf16_f32 v55, v56, v57
	global_store_dwordx4 v[50:51], v[52:55], off
	v_mov_b32_e32 v51, v42
	v_mov_b32_e32 v42, v47
	v_mov_b32_e32 v47, v44
	v_mov_b32_e32 v44, v49
	v_mov_b32_e32 v50, v46
	v_pk_mul_f32 v[42:43], v[42:43], v[42:43]
	v_mov_b32_e32 v46, v48
	v_pk_mul_f32 v[44:45], v[44:45], v[44:45]
	v_pk_fma_f32 v[42:43], v[50:51], v[50:51], v[42:43]
	v_pk_fma_f32 v[44:45], v[46:47], v[46:47], v[44:45]
	s_nop 0
	v_pk_add_f32 v[42:43], v[42:43], v[44:45]
	s_nop 0
	v_add_f32_e32 v42, v42, v43
	v_add_f32_e32 v144, v144, v42
; __device__ __forceinline__ unsigned cvt_pk_bf16(float lo, float hi) { unsigned r; asm volatile("v_cvt_pk_bf16_f32 %0, %1, %2" : "=v"(r) : "v"(lo), "v"(hi)); return r; }
;     __device__ __forceinline__ void operator()(const f32x4 (&acc)[2][2][4][2], const Unit& u, int wr, int wc, int fr, int fq) const {
;     ...
;                 for (int m = 0; m < 4; ++m) { const size_t off = (size_t)(row0 + ai * HALF + m * 16) * 2048 + col0 + bj * HALF;
;                     f32x4 x0 = __builtin_nontemporal_load((const f32x4*)(base + off)), x1 = __builtin_nontemporal_load((const f32x4*)(base + off + 4));
;                     if constexpr (HAS_DIN) { const u32x4 dw = __builtin_nontemporal_load((const u32x4*)(dbuf + off));
;                         x0 += (f32x4){__builtin_bit_cast(float, dw.x << 16), __builtin_bit_cast(float, dw.x & 0xffff0000u), __builtin_bit_cast(float, dw.y << 16), __builtin_bit_cast(float, dw.y & 0xffff0000u)};
;                         x1 += (f32x4){__builtin_bit_cast(float, dw.z << 16), __builtin_bit_cast(float, dw.z & 0xffff0000u), __builtin_bit_cast(float, dw.w << 16), __builtin_bit_cast(float, dw.w & 0xffff0000u)}; }
;                     f32x4 o0, o1;
;                     if constexpr (OUT_DELTA) { const f32x4 d0 = g0 * acc[ai][bj][m][0], d1 = g1 * acc[ai][bj][m][1];
;                         u32x4 w; w.x = cvt_pk_bf16(d0[0], d0[1]); w.y = cvt_pk_bf16(d0[2], d0[3]); w.z = cvt_pk_bf16(d1[0], d1[1]); w.w = cvt_pk_bf16(d1[2], d1[3]);
;                         *(u32x4*)(dbuf + off) = w;
;                         o0 = x0 + (f32x4){__builtin_bit_cast(float, w.x << 16), __builtin_bit_cast(float, w.x & 0xffff0000u), __builtin_bit_cast(float, w.y << 16), __builtin_bit_cast(float, w.y & 0xffff0000u)};
;                         o1 = x1 + (f32x4){__builtin_bit_cast(float, w.z << 16), __builtin_bit_cast(float, w.z & 0xffff0000u), __builtin_bit_cast(float, w.w << 16), __builtin_bit_cast(float, w.w & 0xffff0000u)}; }
;                     else { o0 = x0 + g0 * acc[ai][bj][m][0]; o1 = x1 + g1 * acc[ai][bj][m][1]; *(f32x4*)(out + off) = o0; *(f32x4*)(out + off + 4) = o1; }
;                     if (Hn) { const f32x4 h0 = o0 * G0, h1 = o1 * G1;
;                         u32x4 w; w.x = cvt_pk_bf16(h0[0], h0[1]); w.y = cvt_pk_bf16(h0[2], h0[3]); w.z = cvt_pk_bf16(h1[0], h1[1]); w.w = cvt_pk_bf16(h1[2], h1[3]);
;                         *(u32x4*)(Hn + off) = w;
.LBB0_737:
	s_nop 0
	v_lshl_add_u64 v[42:43], v[114:115], 0, v[156:157]
	v_lshl_add_u64 v[52:53], v[42:43], 1, s[90:91]
	s_and_b64 vcc, exec, s[2:3]
	s_waitcnt vmcnt(7)
	v_mov_b32_e32 v44, v220
	v_mov_b32_e32 v45, v221
	v_mov_b32_e32 v46, v222
	v_mov_b32_e32 v47, v223
	v_mov_b32_e32 v48, v224
	v_mov_b32_e32 v49, v225
	v_mov_b32_e32 v50, v226
	v_mov_b32_e32 v51, v227
	v_mov_b32_e32 v52, v228
	v_mov_b32_e32 v53, v229
	v_mov_b32_e32 v54, v230
	v_mov_b32_e32 v55, v231
	s_mov_b32 s98, 0x140000
	s_mov_b32 s99, 0
	v_lshl_add_u64 v[252:253], v[248:249], 0, s[98:99]
	s_mov_b32 s98, 0xa0000
	v_lshl_add_u64 v[254:255], v[250:251], 0, s[98:99]
	global_load_dwordx4 v[220:223], v[252:253], off offset:528 nt
	global_load_dwordx4 v[224:227], v[252:253], off offset:512 nt
	global_load_dwordx4 v[228:231], v[254:255], off offset:256 nt
	v_lshlrev_b32_e32 v56, 16, v52
	v_and_b32_e32 v57, 0xffff0000, v52
	v_lshlrev_b32_e32 v52, 16, v53
	v_and_b32_e32 v53, 0xffff0000, v53
	v_pk_add_f32 v[50:51], v[50:51], v[52:53]
	v_lshlrev_b32_e32 v52, 16, v54
	v_and_b32_e32 v53, 0xffff0000, v54
	v_lshlrev_b32_e32 v54, 16, v55
	v_and_b32_e32 v55, 0xffff0000, v55
	v_pk_add_f32 v[48:49], v[48:49], v[56:57]
	v_pk_add_f32 v[44:45], v[44:45], v[52:53]
	v_pk_add_f32 v[46:47], v[46:47], v[54:55]
	v_pk_fma_f32 v[32:33], v[32:33], v[40:41], v[50:51]
	v_pk_fma_f32 v[30:31], v[30:31], v[38:39], v[48:49]
	v_pk_fma_f32 v[28:29], v[28:29], v[36:37], v[46:47]
	v_pk_fma_f32 v[26:27], v[26:27], v[34:35], v[44:45]
	global_store_dwordx4 v[118:119], v[30:33], off offset:512
	global_store_dwordx4 v[118:119], v[26:29], off offset:528
	s_cbranch_vccnz .LBB0_739
	v_pk_mul_f32 v[46:47], v[150:151], v[32:33]
	v_pk_mul_f32 v[44:45], v[148:149], v[30:31]
	v_lshl_add_u64 v[42:43], v[42:43], 1, s[96:97]
	v_pk_mul_f32 v[48:49], v[154:155], v[28:29]
	v_pk_mul_f32 v[50:51], v[152:153], v[26:27]
	v_cvt_pk_bf16_f32 v44, v44, v45
	v_cvt_pk_bf16_f32 v45, v46, v47
	s_nop 0
	v_cvt_pk_bf16_f32 v46, v50, v51
	v_cvt_pk_bf16_f32 v47, v48, v49
	global_store_dwordx4 v[42:43], v[44:47], off
	v_mov_b32_e32 v43, v26
	v_mov_b32_e32 v26, v31
	v_mov_b32_e32 v31, v28
	v_mov_b32_e32 v28, v33
	v_mov_b32_e32 v42, v30
	v_pk_mul_f32 v[26:27], v[26:27], v[26:27]
	v_mov_b32_e32 v30, v32
	v_pk_mul_f32 v[28:29], v[28:29], v[28:29]
	v_pk_fma_f32 v[26:27], v[42:43], v[42:43], v[26:27]
	v_pk_fma_f32 v[28:29], v[30:31], v[30:31], v[28:29]
	s_nop 0
	v_pk_add_f32 v[26:27], v[26:27], v[28:29]
	s_nop 0
	v_add_f32_e32 v26, v26, v27
	v_add_f32_e32 v129, v129, v26
.LBB0_739:
	s_nop 0
	v_lshl_add_u64 v[26:27], v[106:107], 0, v[156:157]
	v_lshl_add_u64 v[32:33], v[26:27], 1, s[90:91]
	s_and_b64 vcc, exec, s[2:3]
	s_waitcnt vmcnt(7)
	v_mov_b32_e32 v28, v232
	v_mov_b32_e32 v29, v233
	v_mov_b32_e32 v30, v234
	v_mov_b32_e32 v31, v235
	v_mov_b32_e32 v42, v236
	v_mov_b32_e32 v43, v237
	v_mov_b32_e32 v44, v238
	v_mov_b32_e32 v45, v239
	v_mov_b32_e32 v46, v244
	v_mov_b32_e32 v47, v245
	v_mov_b32_e32 v48, v246
	v_mov_b32_e32 v49, v247
	s_mov_b32 s98, 0x160000
	s_mov_b32 s99, 0
	v_lshl_add_u64 v[252:253], v[248:249], 0, s[98:99]
	s_mov_b32 s98, 0xb0000
	v_lshl_add_u64 v[254:255], v[250:251], 0, s[98:99]
	global_load_dwordx4 v[232:235], v[252:253], off offset:528 nt
	global_load_dwordx4 v[236:239], v[252:253], off offset:512 nt
	global_load_dwordx4 v[244:247], v[254:255], off offset:256 nt
	v_lshlrev_b32_e32 v32, 16, v46
	v_and_b32_e32 v33, 0xffff0000, v46
	v_lshlrev_b32_e32 v46, 16, v47
	v_and_b32_e32 v47, 0xffff0000, v47
	v_pk_add_f32 v[32:33], v[42:43], v[32:33]
	v_pk_add_f32 v[42:43], v[44:45], v[46:47]
	v_lshlrev_b32_e32 v44, 16, v48
	v_and_b32_e32 v45, 0xffff0000, v48
	v_lshlrev_b32_e32 v46, 16, v49
	v_and_b32_e32 v47, 0xffff0000, v49
	v_pk_add_f32 v[28:29], v[28:29], v[44:45]
	v_pk_add_f32 v[30:31], v[30:31], v[46:47]
	v_pk_fma_f32 v[24:25], v[24:25], v[40:41], v[42:43]
	v_pk_fma_f32 v[22:23], v[22:23], v[38:39], v[32:33]
	v_pk_fma_f32 v[20:21], v[20:21], v[36:37], v[30:31]
	v_pk_fma_f32 v[18:19], v[18:19], v[34:35], v[28:29]
	global_store_dwordx4 v[110:111], v[22:25], off offset:512
	global_store_dwordx4 v[110:111], v[18:21], off offset:528
	s_cbranch_vccnz .LBB0_741
	v_pk_mul_f32 v[30:31], v[150:151], v[24:25]
	v_pk_mul_f32 v[28:29], v[148:149], v[22:23]
	v_lshl_add_u64 v[26:27], v[26:27], 1, s[96:97]
	v_pk_mul_f32 v[32:33], v[154:155], v[20:21]
	v_pk_mul_f32 v[42:43], v[152:153], v[18:19]
	v_cvt_pk_bf16_f32 v28, v28, v29
	v_cvt_pk_bf16_f32 v29, v30, v31
	s_nop 0
	v_cvt_pk_bf16_f32 v30, v42, v43
	v_cvt_pk_bf16_f32 v31, v32, v33
	global_store_dwordx4 v[26:27], v[28:31], off
	v_mov_b32_e32 v27, v18
	v_mov_b32_e32 v18, v23
	v_mov_b32_e32 v23, v20
	v_mov_b32_e32 v20, v25
	v_mov_b32_e32 v26, v22
	v_pk_mul_f32 v[18:19], v[18:19], v[18:19]
	v_mov_b32_e32 v22, v24
	v_pk_mul_f32 v[20:21], v[20:21], v[20:21]
	v_pk_fma_f32 v[18:19], v[26:27], v[26:27], v[18:19]
	v_pk_fma_f32 v[20:21], v[22:23], v[22:23], v[20:21]
	s_nop 0
	v_pk_add_f32 v[18:19], v[18:19], v[20:21]
	s_nop 0
	v_add_f32_e32 v18, v18, v19
	v_add_f32_e32 v128, v128, v18
; __device__ __forceinline__ unsigned cvt_pk_bf16(float lo, float hi) { unsigned r; asm volatile("v_cvt_pk_bf16_f32 %0, %1, %2" : "=v"(r) : "v"(lo), "v"(hi)); return r; }
;     __device__ __forceinline__ void operator()(const f32x4 (&acc)[2][2][4][2], const Unit& u, int wr, int wc, int fr, int fq) const {
;     ...
;                 for (int m = 0; m < 4; ++m) { const size_t off = (size_t)(row0 + ai * HALF + m * 16) * 2048 + col0 + bj * HALF;
;                     f32x4 x0 = __builtin_nontemporal_load((const f32x4*)(base + off)), x1 = __builtin_nontemporal_load((const f32x4*)(base + off + 4));
;                     if constexpr (HAS_DIN) { const u32x4 dw = __builtin_nontemporal_load((const u32x4*)(dbuf + off));
;                         x0 += (f32x4){__builtin_bit_cast(float, dw.x << 16), __builtin_bit_cast(float, dw.x & 0xffff0000u), __builtin_bit_cast(float, dw.y << 16), __builtin_bit_cast(float, dw.y & 0xffff0000u)};
;                         x1 += (f32x4){__builtin_bit_cast(float, dw.z << 16), __builtin_bit_cast(float, dw.z & 0xffff0000u), __builtin_bit_cast(float, dw.w << 16), __builtin_bit_cast(float, dw.w & 0xffff0000u)}; }
;                     f32x4 o0, o1;
;                     if constexpr (OUT_DELTA) { const f32x4 d0 = g0 * acc[ai][bj][m][0], d1 = g1 * acc[ai][bj][m][1];
;                         u32x4 w; w.x = cvt_pk_bf16(d0[0], d0[1]); w.y = cvt_pk_bf16(d0[2], d0[3]); w.z = cvt_pk_bf16(d1[0], d1[1]); w.w = cvt_pk_bf16(d1[2], d1[3]);
;                         *(u32x4*)(dbuf + off) = w;
;                         o0 = x0 + (f32x4){__builtin_bit_cast(float, w.x << 16), __builtin_bit_cast(float, w.x & 0xffff0000u), __builtin_bit_cast(float, w.y << 16), __builtin_bit_cast(float, w.y & 0xffff0000u)};
;                         o1 = x1 + (f32x4){__builtin_bit_cast(float, w.z << 16), __builtin_bit_cast(float, w.z & 0xffff0000u), __builtin_bit_cast(float, w.w << 16), __builtin_bit_cast(float, w.w & 0xffff0000u)}; }
;                     else { o0 = x0 + g0 * acc[ai][bj][m][0]; o1 = x1 + g1 * acc[ai][bj][m][1]; *(f32x4*)(out + off) = o0; *(f32x4*)(out + off + 4) = o1; }
;                     if (Hn) { const f32x4 h0 = o0 * G0, h1 = o1 * G1;
;                         u32x4 w; w.x = cvt_pk_bf16(h0[0], h0[1]); w.y = cvt_pk_bf16(h0[2], h0[3]); w.z = cvt_pk_bf16(h1[0], h1[1]); w.w = cvt_pk_bf16(h1[2], h1[3]);
;                         *(u32x4*)(Hn + off) = w;
.LBB0_741:
	s_nop 0
	v_lshl_add_u64 v[18:19], v[90:91], 0, v[156:157]
	v_lshl_add_u64 v[28:29], v[18:19], 1, s[90:91]
	s_and_b64 vcc, exec, s[2:3]
	s_waitcnt vmcnt(7)
	v_mov_b32_e32 v20, v220
	v_mov_b32_e32 v21, v221
	v_mov_b32_e32 v22, v222
	v_mov_b32_e32 v23, v223
	v_mov_b32_e32 v24, v224
	v_mov_b32_e32 v25, v225
	v_mov_b32_e32 v26, v226
	v_mov_b32_e32 v27, v227
	v_mov_b32_e32 v28, v228
	v_mov_b32_e32 v29, v229
	v_mov_b32_e32 v30, v230
	v_mov_b32_e32 v31, v231
	v_lshlrev_b32_e32 v32, 16, v28
	v_and_b32_e32 v33, 0xffff0000, v28
	v_lshlrev_b32_e32 v28, 16, v29
	v_and_b32_e32 v29, 0xffff0000, v29
	v_pk_add_f32 v[26:27], v[26:27], v[28:29]
	v_lshlrev_b32_e32 v28, 16, v30
	v_and_b32_e32 v29, 0xffff0000, v30
	v_lshlrev_b32_e32 v30, 16, v31
	v_and_b32_e32 v31, 0xffff0000, v31
	v_pk_add_f32 v[24:25], v[24:25], v[32:33]
	v_pk_add_f32 v[20:21], v[20:21], v[28:29]
	v_pk_add_f32 v[22:23], v[22:23], v[30:31]
	v_pk_fma_f32 v[16:17], v[16:17], v[40:41], v[26:27]
	v_pk_fma_f32 v[14:15], v[14:15], v[38:39], v[24:25]
	v_pk_fma_f32 v[12:13], v[12:13], v[36:37], v[22:23]
	v_pk_fma_f32 v[10:11], v[10:11], v[34:35], v[20:21]
	global_store_dwordx4 v[94:95], v[14:17], off offset:512
	global_store_dwordx4 v[94:95], v[10:13], off offset:528
	s_cbranch_vccnz .LBB0_743
	v_pk_mul_f32 v[22:23], v[150:151], v[16:17]
	v_pk_mul_f32 v[20:21], v[148:149], v[14:15]
	v_lshl_add_u64 v[18:19], v[18:19], 1, s[96:97]
	v_pk_mul_f32 v[24:25], v[154:155], v[12:13]
	v_pk_mul_f32 v[26:27], v[152:153], v[10:11]
	v_cvt_pk_bf16_f32 v20, v20, v21
	v_cvt_pk_bf16_f32 v21, v22, v23
	s_nop 0
	v_cvt_pk_bf16_f32 v22, v26, v27
	v_cvt_pk_bf16_f32 v23, v24, v25
	global_store_dwordx4 v[18:19], v[20:23], off
	v_mov_b32_e32 v19, v10
	v_mov_b32_e32 v10, v15
	v_mov_b32_e32 v15, v12
	v_mov_b32_e32 v12, v17
	v_mov_b32_e32 v18, v14
	v_pk_mul_f32 v[10:11], v[10:11], v[10:11]
	v_mov_b32_e32 v14, v16
	v_pk_mul_f32 v[12:13], v[12:13], v[12:13]
	v_pk_fma_f32 v[10:11], v[18:19], v[18:19], v[10:11]
	v_pk_fma_f32 v[12:13], v[14:15], v[14:15], v[12:13]
	s_nop 0
	v_pk_add_f32 v[10:11], v[10:11], v[12:13]
	s_nop 0
	v_add_f32_e32 v10, v10, v11
	v_add_f32_e32 v113, v113, v10
.LBB0_743:
	s_nop 0
	v_lshl_add_u64 v[10:11], v[82:83], 0, v[156:157]
	v_lshl_add_u64 v[20:21], v[10:11], 1, s[90:91]
	s_and_b64 vcc, exec, s[2:3]
	s_waitcnt vmcnt(4)
	v_mov_b32_e32 v12, v232
	v_mov_b32_e32 v13, v233
	v_mov_b32_e32 v14, v234
	v_mov_b32_e32 v15, v235
	v_mov_b32_e32 v16, v236
	v_mov_b32_e32 v17, v237
	v_mov_b32_e32 v18, v238
	v_mov_b32_e32 v19, v239
	v_mov_b32_e32 v20, v244
	v_mov_b32_e32 v21, v245
	v_mov_b32_e32 v22, v246
	v_mov_b32_e32 v23, v247
	v_lshlrev_b32_e32 v24, 16, v20
	v_and_b32_e32 v25, 0xffff0000, v20
	v_lshlrev_b32_e32 v20, 16, v21
	v_and_b32_e32 v21, 0xffff0000, v21
	v_pk_add_f32 v[18:19], v[18:19], v[20:21]
	v_lshlrev_b32_e32 v20, 16, v22
	v_and_b32_e32 v21, 0xffff0000, v22
	v_lshlrev_b32_e32 v22, 16, v23
	v_and_b32_e32 v23, 0xffff0000, v23
	v_pk_add_f32 v[16:17], v[16:17], v[24:25]
	v_pk_add_f32 v[12:13], v[12:13], v[20:21]
	v_pk_add_f32 v[14:15], v[14:15], v[22:23]
	v_pk_fma_f32 v[8:9], v[8:9], v[40:41], v[18:19]
	v_pk_fma_f32 v[6:7], v[6:7], v[38:39], v[16:17]
	v_pk_fma_f32 v[4:5], v[4:5], v[36:37], v[14:15]
	v_pk_fma_f32 v[2:3], v[2:3], v[34:35], v[12:13]
	global_store_dwordx4 v[86:87], v[6:9], off offset:512
	global_store_dwordx4 v[86:87], v[2:5], off offset:528
	s_cbranch_vccnz .LBB0_695
	v_pk_mul_f32 v[12:13], v[150:151], v[8:9]
	v_pk_mul_f32 v[14:15], v[148:149], v[6:7]
	v_pk_mul_f32 v[18:19], v[152:153], v[2:3]
	v_cvt_pk_bf16_f32 v16, v14, v15
	v_cvt_pk_bf16_f32 v17, v12, v13
	v_and_b32_e32 v13, 64, v218
	v_xor_b32_e32 v12, 16, v218
	v_add_u32_e32 v13, 64, v13
	v_cmp_lt_i32_e32 vcc, v12, v13
	v_xor_b32_e32 v15, 32, v218
	v_lshl_add_u64 v[10:11], v[10:11], 1, s[96:97]
	v_cndmask_b32_e32 v12, v218, v12, vcc
	v_lshlrev_b32_e32 v12, 2, v12
	ds_bpermute_b32 v14, v12, v196
	v_cmp_lt_i32_e32 vcc, v15, v13
	v_pk_mul_f32 v[20:21], v[154:155], v[4:5]
	v_cvt_pk_bf16_f32 v18, v18, v19
	s_waitcnt lgkmcnt(0)
	v_add_f32_e32 v14, v196, v14
	v_cndmask_b32_e32 v13, v218, v15, vcc
	v_lshlrev_b32_e32 v13, 2, v13
	ds_bpermute_b32 v15, v13, v14
	v_cvt_pk_bf16_f32 v19, v20, v21
	global_store_dwordx4 v[10:11], v[16:19], off
	v_lshl_add_u64 v[10:11], v[146:147], 3, s[50:51]
	s_and_saveexec_b64 s[2:3], s[36:37]
	s_cbranch_execz .LBB0_746
	s_waitcnt lgkmcnt(0)
	v_add_f32_e32 v14, v14, v15
	v_mul_f32_e32 v14, 0x47800000, v14
	v_rndne_f32_e32 v14, v14
	v_mul_f32_e64 v15, |v14|, s40
	v_floor_f32_e32 v15, v15
	v_fma_f32 v16, v15, s6, |v14|
	v_cvt_u32_f32_e32 v16, v16
	v_cvt_u32_f32_e32 v15, v15
	v_ashrrev_i32_e32 v17, 31, v14
	v_xor_b32_e32 v14, v16, v17
	v_xor_b32_e32 v15, v15, v17
	v_sub_co_u32_e32 v14, vcc, v14, v17
	s_nop 1
	v_subb_co_u32_e32 v15, vcc, v15, v17, vcc
	global_atomic_add_x2 v[10:11], v[14:15], off

; __global__ void __launch_bounds__(NWAVES * 64, 2) skel_fwd(Args args) {
;     extern __shared__ __attribute__((aligned(16))) unsigned char lds[];
	.amdhsa_kernel _Z8skel_fwd4Args
		.amdhsa_group_segment_fixed_size 0
		.amdhsa_private_segment_fixed_size 0
		.amdhsa_kernarg_size 408
		.amdhsa_user_sgpr_count 2
		.amdhsa_user_sgpr_dispatch_ptr 0
		.amdhsa_user_sgpr_queue_ptr 0
		.amdhsa_user_sgpr_kernarg_segment_ptr 1
		.amdhsa_user_sgpr_dispatch_id 0
		.amdhsa_user_sgpr_kernarg_preload_length 0
		.amdhsa_user_sgpr_kernarg_preload_offset 0
		.amdhsa_user_sgpr_private_segment_size 0
		.amdhsa_uses_dynamic_stack 0
		.amdhsa_enable_private_segment 0
		.amdhsa_system_sgpr_workgroup_id_x 1
		.amdhsa_system_sgpr_workgroup_id_y 0
		.amdhsa_system_sgpr_workgroup_id_z 0
		.amdhsa_system_sgpr_workgroup_info 0
		.amdhsa_system_vgpr_workitem_id 0
		.amdhsa_next_free_vgpr 256
		.amdhsa_next_free_sgpr 102
		.amdhsa_accum_offset 256
		.amdhsa_reserve_vcc 1
		.amdhsa_float_round_mode_32 0
		.amdhsa_float_round_mode_16_64 0
		.amdhsa_float_denorm_mode_32 3
		.amdhsa_float_denorm_mode_16_64 3
		.amdhsa_dx10_clamp 1
		.amdhsa_ieee_mode 1
		.amdhsa_fp16_overflow 0
		.amdhsa_tg_split 0
		.amdhsa_exception_fp_ieee_invalid_op 0
		.amdhsa_exception_fp_denorm_src 0
		.amdhsa_exception_fp_ieee_div_zero 0
		.amdhsa_exception_fp_ieee_overflow 0
		.amdhsa_exception_fp_ieee_underflow 0
		.amdhsa_exception_fp_ieee_inexact 0
		.amdhsa_exception_int_div_zero 0
	.end_amdhsa_kernel

; __global__ void __launch_bounds__(NWAVES * 64, 2) skel_fwd(Args args) {
;     extern __shared__ __attribute__((aligned(16))) unsigned char lds[];
amdhsa.kernels:
  - .agpr_count:     0
    .args:
      - .offset:         0
        .size:           152
        .value_kind:     by_value
      - .offset:         152
        .size:           4
        .value_kind:     hidden_block_count_x
      - .offset:         156
        .size:           4
        .value_kind:     hidden_block_count_y
      - .offset:         160
        .size:           4
        .value_kind:     hidden_block_count_z
      - .offset:         164
        .size:           2
        .value_kind:     hidden_group_size_x
      - .offset:         166
        .size:           2
        .value_kind:     hidden_group_size_y
      - .offset:         168
        .size:           2
        .value_kind:     hidden_group_size_z
      - .offset:         170
        .size:           2
        .value_kind:     hidden_remainder_x
      - .offset:         172
        .size:           2
        .value_kind:     hidden_remainder_y
      - .offset:         174
        .size:           2
        .value_kind:     hidden_remainder_z
      - .offset:         192
        .size:           8
        .value_kind:     hidden_global_offset_x
      - .offset:         200
        .size:           8
        .value_kind:     hidden_global_offset_y
      - .offset:         208
        .size:           8
        .value_kind:     hidden_global_offset_z
      - .offset:         216
        .size:           2
        .value_kind:     hidden_grid_dims
      - .offset:         272
        .size:           4
        .value_kind:     hidden_dynamic_lds_size
    .group_segment_fixed_size: 0
    .kernarg_segment_align: 8
    .kernarg_segment_size: 408
    .language:       OpenCL C
    .language_version:
      - 2
      - 0
    .max_flat_workgroup_size: 512
    .name:           _Z8skel_fwd4Args
    .private_segment_fixed_size: 0
    .sgpr_count:     108
    .sgpr_spill_count: 247
    .symbol:         _Z8skel_fwd4Args.kd
    .uniform_work_group_size: 1
    .uses_dynamic_stack: false
    .vgpr_count:     256
    .vgpr_spill_count: 0
    .wavefront_size: 64
